# first K iteration of each tile peeled in PG/PH/Vt/GLU/S3 GEMMs: its first MFMA per accumulator takes SrcC=0, the 128 accumulator-clearing v_mov per tile removed
# speedup vs baseline: 1.0064x; 1.0064x over previous
; #define PG8_STAGE(bufoff, gbase, voff) do { _Pragma("unroll") for (int _i = 0; _i < 2; ++_i) \
;         __builtin_amdgcn_global_load_lds((const unsigned*)((const char*)(gbase) + (voff)[_i]), (LAS unsigned*)(lds + (bufoff) + ldsw + _i * 8192), 16, 0, 0); } while (0)
; #define PG8_LDA(dst, b, h) do { _Pragma("unroll") for (int m = 0; m < 4; ++m) _Pragma("unroll") for (int k = 0; k < 2; ++k) dst[m][k] = *(const LAS bf16x8*)(lds + PG8_SA(b, h) + aoff + m * 2048 + k * 1024); } while (0)
; #define PG8_LDB(dst, b, h) do { _Pragma("unroll") for (int n = 0; n < 2; ++n) _Pragma("unroll") for (int k = 0; k < 2; ++k) dst[n][k] = *(const LAS bf16x8*)(lds + PG8_SB(b, h) + boff + n * 2048 + k * 1024); } while (0)
; #define PG8_MMA(ai, bj, At, Bt) do { __builtin_amdgcn_s_setprio(1); _Pragma("unroll") for (int m = 0; m < 4; ++m) _Pragma("unroll") for (int n = 0; n < 2; ++n) _Pragma("unroll") for (int k = 0; k < 2; ++k) \
;         acc[ai][bj][m][n] = __builtin_amdgcn_mfma_f32_16x16x32_bf16(Bt[n][k], At[m][k], acc[ai][bj][m][n], 0, 0, 0); __builtin_amdgcn_s_setprio(0); } while (0)
; #define PG8_WAIT_V(n) asm volatile("s_waitcnt vmcnt(" #n ")" ::: "memory")
; #define PG8_WAIT_L(n) asm volatile("s_waitcnt lgkmcnt(" #n ")" ::: "memory")
; #define PG8_BAR __builtin_amdgcn_s_barrier()
; #define PG8_SCHED __builtin_amdgcn_sched_barrier(0)
; template <class Epi, class Sched, bool ALIGN_EPI>
; __device__ __forceinline__ void gemm_phase(LAS unsigned char* lds, const Gemm g, const Sched& S, const Epi& E) {
;     ...
;             PG8_LDB(B0, 0, 0); PG8_LDB(B1, 0, 1); PG8_SCHED; PG8_LDA(At, 0, 0); PG8_STAGE(PG8_SA(1, 1), a1 + hstepA, voffA);
;             PG8_WAIT_V(8); PG8_WAIT_L(0); PG8_BAR; PG8_MMA(0, 0, At, B0); PG8_MMA(0, 1, At, B1); PG8_BAR; PG8_SCHED;
;             PG8_LDA(At, 0, 1); PG8_STAGE(PG8_SB(0, 0), b2, voffB); PG8_STAGE(PG8_SB(0, 1), b2 + hstepB, voffB); PG8_STAGE(PG8_SA(0, 0), a2, voffA);
;     ...
;         for (int a = 0; a < 2; ++a)
; #pragma unroll
;             for (int b = 0; b < 2; ++b)
; #pragma unroll
;                 for (int m = 0; m < 4; ++m)
; #pragma unroll
;                     for (int n = 0; n < 2; ++n) acc[a][b][m][n] = (f32x4){0.f, 0.f, 0.f, 0.f};
;         cur = nxt; cA = nA; cB = nB; ++ui;
.LBB0_208:
	s_ashr_i32 s81, s80, 31
	s_lshl_b64 s[54:55], s[80:81], 21
	s_add_u32 s84, s33, s54
	s_addc_u32 s85, s51, s55
	s_and_b64 s[54:55], s[42:43], exec
	s_cselect_b32 s56, s85, s45
	s_cselect_b32 s57, s84, s44
	s_ashr_i32 s63, s62, 31
	s_lshl_b64 s[54:55], s[62:63], 21
	v_readlane_b32 s52, v255, 48
	s_add_u32 s90, s52, s54
	s_addc_u32 s91, s48, s55
	s_and_b64 s[54:55], s[42:43], exec
	s_cselect_b32 s63, s91, s47
	s_cselect_b32 s64, s90, s46
	s_add_u32 s44, s44, 0x100080
	s_addc_u32 s45, s45, 0
	s_add_u32 s65, s46, 0x100
	s_addc_u32 s81, s47, 0
	s_mov_b32 s92, -2
	s_add_u32 s46, s44, 0xfff00080
	s_addc_u32 s47, s45, -1
	s_add_i32 s52, 0, 0x10000
	s_cmp_eq_u32 s92, 60
	s_cselect_b32 s55, s56, s47
	s_cselect_b32 s54, s57, s46
	s_cselect_b32 s47, s63, s81
	s_cselect_b32 s46, s64, s65
	s_add_i32 s53, 0, 0x14000
	v_add_u32_e32 v140, s52, v247
	v_add_u32_e32 v156, s53, v247
	ds_read_b128 v[104:107], v140
	ds_read_b128 v[112:115], v140 offset:1024
	ds_read_b128 v[136:139], v140 offset:2048
	ds_read_b128 v[140:143], v140 offset:3072
	ds_read_b128 v[144:147], v156
	ds_read_b128 v[148:151], v156 offset:1024
	ds_read_b128 v[152:155], v156 offset:2048
	ds_read_b128 v[156:159], v156 offset:3072
	v_lshl_add_u64 v[194:195], s[44:45], 0, v[220:221]
	s_add_i32 m0, s49, 0xc000
	ds_read_b128 v[160:163], v248
	ds_read_b128 v[164:167], v248 offset:1024
	ds_read_b128 v[168:171], v248 offset:2048
	ds_read_b128 v[172:175], v248 offset:3072
	ds_read_b128 v[176:179], v248 offset:4096
	ds_read_b128 v[180:183], v248 offset:5120
	ds_read_b128 v[184:187], v248 offset:6144
	ds_read_b128 v[188:191], v248 offset:7168
	global_load_lds_dwordx4 v[194:195], off
	v_lshl_add_u64 v[194:195], s[44:45], 0, v[222:223]
	s_add_i32 m0, s49, 0xe000
	s_nop 0
	global_load_lds_dwordx4 v[194:195], off
	s_waitcnt vmcnt(8)
	s_waitcnt lgkmcnt(0)
	s_barrier
	s_setprio 1
	s_waitcnt lgkmcnt(0)
	v_mfma_f32_16x16x32_bf16 v[132:135], v[104:107], v[160:163], 0
	v_mfma_f32_16x16x32_bf16 v[128:131], v[136:139], v[160:163], 0
	v_mfma_f32_16x16x32_bf16 v[116:119], v[104:107], v[168:171], 0
	v_mfma_f32_16x16x32_bf16 v[108:111], v[136:139], v[168:171], 0
	v_mfma_f32_16x16x32_bf16 v[96:99], v[104:107], v[176:179], 0
	v_mfma_f32_16x16x32_bf16 v[88:91], v[136:139], v[176:179], 0
	v_mfma_f32_16x16x32_bf16 v[80:83], v[104:107], v[184:187], 0
	v_mfma_f32_16x16x32_bf16 v[72:75], v[136:139], v[184:187], 0
	v_mfma_f32_16x16x32_bf16 v[132:135], v[112:115], v[164:167], v[132:135]
	v_mfma_f32_16x16x32_bf16 v[128:131], v[140:143], v[164:167], v[128:131]
	v_mfma_f32_16x16x32_bf16 v[116:119], v[112:115], v[172:175], v[116:119]
	v_mfma_f32_16x16x32_bf16 v[108:111], v[140:143], v[172:175], v[108:111]
	v_mfma_f32_16x16x32_bf16 v[96:99], v[112:115], v[180:183], v[96:99]
	v_mfma_f32_16x16x32_bf16 v[88:91], v[140:143], v[180:183], v[88:91]
	v_mfma_f32_16x16x32_bf16 v[80:83], v[112:115], v[188:191], v[80:83]
	v_mfma_f32_16x16x32_bf16 v[72:75], v[140:143], v[188:191], v[72:75]
	s_setprio 0
	s_setprio 1
	v_mfma_f32_16x16x32_bf16 v[124:127], v[144:147], v[160:163], 0
	v_mfma_f32_16x16x32_bf16 v[120:123], v[152:155], v[160:163], 0
	v_mfma_f32_16x16x32_bf16 v[100:103], v[144:147], v[168:171], 0
	v_mfma_f32_16x16x32_bf16 v[92:95], v[152:155], v[168:171], 0
	v_mfma_f32_16x16x32_bf16 v[84:87], v[144:147], v[176:179], 0
	v_mfma_f32_16x16x32_bf16 v[76:79], v[152:155], v[176:179], 0
	v_mfma_f32_16x16x32_bf16 v[68:71], v[144:147], v[184:187], 0
	v_mfma_f32_16x16x32_bf16 v[64:67], v[152:155], v[184:187], 0
	v_mfma_f32_16x16x32_bf16 v[124:127], v[148:151], v[164:167], v[124:127]
	v_mfma_f32_16x16x32_bf16 v[120:123], v[156:159], v[164:167], v[120:123]
	v_mfma_f32_16x16x32_bf16 v[100:103], v[148:151], v[172:175], v[100:103]
	v_mfma_f32_16x16x32_bf16 v[92:95], v[156:159], v[172:175], v[92:95]
	v_mfma_f32_16x16x32_bf16 v[84:87], v[148:151], v[180:183], v[84:87]
	v_mfma_f32_16x16x32_bf16 v[76:79], v[156:159], v[180:183], v[76:79]
	v_mfma_f32_16x16x32_bf16 v[68:71], v[148:151], v[188:191], v[68:71]
	v_mfma_f32_16x16x32_bf16 v[64:67], v[156:159], v[188:191], v[64:67]
	s_setprio 0
	s_barrier
	s_add_i32 s52, s52, s50
	v_lshl_add_u64 v[194:195], s[46:47], 0, v[216:217]
	s_mov_b32 m0, s52
	ds_read_b128 v[160:163], v248 offset:16384
	ds_read_b128 v[164:167], v248 offset:17408
	ds_read_b128 v[168:171], v248 offset:18432
	ds_read_b128 v[172:175], v248 offset:19456
	ds_read_b128 v[176:179], v248 offset:20480
	ds_read_b128 v[180:183], v248 offset:21504
	ds_read_b128 v[184:187], v248 offset:22528
	ds_read_b128 v[188:191], v248 offset:23552
	global_load_lds_dwordx4 v[194:195], off
	s_add_i32 m0, s52, 0x2000
	s_add_u32 vcc_lo, s46, 0x100000
	v_lshl_add_u64 v[196:197], s[46:47], 0, v[212:213]
	s_addc_u32 vcc_hi, s47, 0
	s_add_i32 s52, s53, s50
	global_load_lds_dwordx4 v[196:197], off
	v_lshl_add_u64 v[198:199], vcc, 0, v[216:217]
	s_mov_b32 m0, s52
	v_lshl_add_u64 v[200:201], s[54:55], 0, v[214:215]
	global_load_lds_dwordx4 v[198:199], off
	v_lshl_add_u64 v[198:199], vcc, 0, v[212:213]
	s_add_i32 m0, s52, 0x2000
	s_nop 0
	global_load_lds_dwordx4 v[198:199], off
	v_lshl_add_u64 v[198:199], s[54:55], 0, v[218:219]
	s_mov_b32 m0, s49
	s_nop 0
	global_load_lds_dwordx4 v[198:199], off
	s_mov_b32 m0, s67
	s_nop 0
	global_load_lds_dwordx4 v[200:201], off
	s_waitcnt vmcnt(8)
	s_waitcnt lgkmcnt(0)
	s_barrier
; #define PG8_STAGE(bufoff, gbase, voff) do { _Pragma("unroll") for (int _i = 0; _i < 2; ++_i) \
;         __builtin_amdgcn_global_load_lds((const unsigned*)((const char*)(gbase) + (voff)[_i]), (LAS unsigned*)(lds + (bufoff) + ldsw + _i * 8192), 16, 0, 0); } while (0)
; #define PG8_LDA(dst, b, h) do { _Pragma("unroll") for (int m = 0; m < 4; ++m) _Pragma("unroll") for (int k = 0; k < 2; ++k) dst[m][k] = *(const LAS bf16x8*)(lds + PG8_SA(b, h) + aoff + m * 2048 + k * 1024); } while (0)
; #define PG8_LDB(dst, b, h) do { _Pragma("unroll") for (int n = 0; n < 2; ++n) _Pragma("unroll") for (int k = 0; k < 2; ++k) dst[n][k] = *(const LAS bf16x8*)(lds + PG8_SB(b, h) + boff + n * 2048 + k * 1024); } while (0)
; #define PG8_MMA(ai, bj, At, Bt) do { __builtin_amdgcn_s_setprio(1); _Pragma("unroll") for (int m = 0; m < 4; ++m) _Pragma("unroll") for (int n = 0; n < 2; ++n) _Pragma("unroll") for (int k = 0; k < 2; ++k) \
;         acc[ai][bj][m][n] = __builtin_amdgcn_mfma_f32_16x16x32_bf16(Bt[n][k], At[m][k], acc[ai][bj][m][n], 0, 0, 0); __builtin_amdgcn_s_setprio(0); } while (0)
; #define PG8_WAIT_V(n) asm volatile("s_waitcnt vmcnt(" #n ")" ::: "memory")
; #define PG8_WAIT_L(n) asm volatile("s_waitcnt lgkmcnt(" #n ")" ::: "memory")
; #define PG8_BAR __builtin_amdgcn_s_barrier()
; #define PG8_SCHED __builtin_amdgcn_sched_barrier(0)
; template <class Epi, class Sched, bool ALIGN_EPI>
; __device__ __forceinline__ void gemm_phase(LAS unsigned char* lds, const Gemm g, const Sched& S, const Epi& E) {
;     ...
;             PG8_WAIT_V(8); PG8_WAIT_L(0); PG8_BAR; PG8_MMA(1, 0, At, B0); PG8_MMA(1, 1, At, B1); PG8_BAR; PG8_SCHED;
;             PG8_LDB(B0, 1, 0); PG8_LDB(B1, 1, 1); PG8_SCHED; PG8_LDA(At, 1, 0); PG8_STAGE(PG8_SA(0, 1), a2 + hstepA, voffA);
;             PG8_WAIT_V(8); PG8_WAIT_L(0); PG8_BAR; PG8_MMA(0, 0, At, B0); PG8_MMA(0, 1, At, B1); PG8_BAR; PG8_SCHED;
	s_setprio 1
	s_waitcnt lgkmcnt(0)
	v_mfma_f32_16x16x32_bf16 v[60:63], v[104:107], v[160:163], 0
	v_mfma_f32_16x16x32_bf16 v[56:59], v[136:139], v[160:163], 0
	v_mfma_f32_16x16x32_bf16 v[44:47], v[104:107], v[168:171], 0
	v_mfma_f32_16x16x32_bf16 v[40:43], v[136:139], v[168:171], 0
	v_mfma_f32_16x16x32_bf16 v[32:35], v[104:107], v[176:179], 0
	v_mfma_f32_16x16x32_bf16 v[24:27], v[136:139], v[176:179], 0
	v_mfma_f32_16x16x32_bf16 v[16:19], v[104:107], v[184:187], 0
	v_mfma_f32_16x16x32_bf16 v[8:11], v[136:139], v[184:187], 0
	v_mfma_f32_16x16x32_bf16 v[60:63], v[112:115], v[164:167], v[60:63]
	v_mfma_f32_16x16x32_bf16 v[56:59], v[140:143], v[164:167], v[56:59]
	v_mfma_f32_16x16x32_bf16 v[44:47], v[112:115], v[172:175], v[44:47]
	v_mfma_f32_16x16x32_bf16 v[40:43], v[140:143], v[172:175], v[40:43]
	v_mfma_f32_16x16x32_bf16 v[32:35], v[112:115], v[180:183], v[32:35]
	v_mfma_f32_16x16x32_bf16 v[24:27], v[140:143], v[180:183], v[24:27]
	v_mfma_f32_16x16x32_bf16 v[16:19], v[112:115], v[188:191], v[16:19]
	v_mfma_f32_16x16x32_bf16 v[8:11], v[140:143], v[188:191], v[8:11]
	s_setprio 0
	s_setprio 1
	v_mfma_f32_16x16x32_bf16 v[52:55], v[144:147], v[160:163], 0
	v_mfma_f32_16x16x32_bf16 v[48:51], v[152:155], v[160:163], 0
	v_mfma_f32_16x16x32_bf16 v[36:39], v[144:147], v[168:171], 0
	v_mfma_f32_16x16x32_bf16 v[28:31], v[152:155], v[168:171], 0
	v_mfma_f32_16x16x32_bf16 v[20:23], v[144:147], v[176:179], 0
	v_mfma_f32_16x16x32_bf16 v[12:15], v[152:155], v[176:179], 0
	v_mfma_f32_16x16x32_bf16 v[4:7], v[144:147], v[184:187], 0
	v_mfma_f32_16x16x32_bf16 v[0:3], v[152:155], v[184:187], 0
	v_mfma_f32_16x16x32_bf16 v[52:55], v[148:151], v[164:167], v[52:55]
	v_mfma_f32_16x16x32_bf16 v[48:51], v[156:159], v[164:167], v[48:51]
	v_mfma_f32_16x16x32_bf16 v[36:39], v[148:151], v[172:175], v[36:39]
	v_mfma_f32_16x16x32_bf16 v[28:31], v[156:159], v[172:175], v[28:31]
	v_mfma_f32_16x16x32_bf16 v[20:23], v[148:151], v[180:183], v[20:23]
	v_mfma_f32_16x16x32_bf16 v[12:15], v[156:159], v[180:183], v[12:15]
	v_mfma_f32_16x16x32_bf16 v[4:7], v[148:151], v[188:191], v[4:7]
	v_mfma_f32_16x16x32_bf16 v[0:3], v[156:159], v[188:191], v[0:3]
	s_setprio 0
	s_barrier
	s_add_i32 s52, 0, 0x18000
	s_add_i32 s53, 0, 0x1c000
	v_add_u32_e32 v140, s52, v247
	v_add_u32_e32 v156, s53, v247
	ds_read_b128 v[104:107], v140
	ds_read_b128 v[112:115], v140 offset:1024
	ds_read_b128 v[136:139], v140 offset:2048
	ds_read_b128 v[140:143], v140 offset:3072
	ds_read_b128 v[144:147], v156
	ds_read_b128 v[148:151], v156 offset:1024
	ds_read_b128 v[152:155], v156 offset:2048
	ds_read_b128 v[156:159], v156 offset:3072
	s_add_u32 s54, s54, 0x100000
	s_addc_u32 s55, s55, 0
	s_mov_b32 m0, s86
	v_lshl_add_u64 v[202:203], s[54:55], 0, v[218:219]
	ds_read_b128 v[160:163], v248 offset:32768
	ds_read_b128 v[164:167], v248 offset:33792
	ds_read_b128 v[168:171], v248 offset:34816
	ds_read_b128 v[172:175], v248 offset:35840
	ds_read_b128 v[176:179], v248 offset:36864
	ds_read_b128 v[180:183], v248 offset:37888
	ds_read_b128 v[184:187], v248 offset:38912
	ds_read_b128 v[188:191], v248 offset:39936
	global_load_lds_dwordx4 v[202:203], off
	v_lshl_add_u64 v[202:203], s[54:55], 0, v[214:215]
	s_mov_b32 m0, s66
	s_nop 0
	global_load_lds_dwordx4 v[202:203], off
	s_waitcnt vmcnt(8)
	s_waitcnt lgkmcnt(0)
	s_barrier
	s_setprio 1
	s_waitcnt lgkmcnt(0)
	v_mfma_f32_16x16x32_bf16 v[132:135], v[104:107], v[160:163], v[132:135]
	v_mfma_f32_16x16x32_bf16 v[128:131], v[136:139], v[160:163], v[128:131]
	v_mfma_f32_16x16x32_bf16 v[116:119], v[104:107], v[168:171], v[116:119]
	v_mfma_f32_16x16x32_bf16 v[108:111], v[136:139], v[168:171], v[108:111]
	v_mfma_f32_16x16x32_bf16 v[96:99], v[104:107], v[176:179], v[96:99]
	v_mfma_f32_16x16x32_bf16 v[88:91], v[136:139], v[176:179], v[88:91]
	v_mfma_f32_16x16x32_bf16 v[80:83], v[104:107], v[184:187], v[80:83]
	v_mfma_f32_16x16x32_bf16 v[72:75], v[136:139], v[184:187], v[72:75]
	v_mfma_f32_16x16x32_bf16 v[132:135], v[112:115], v[164:167], v[132:135]
	v_mfma_f32_16x16x32_bf16 v[128:131], v[140:143], v[164:167], v[128:131]
	v_mfma_f32_16x16x32_bf16 v[116:119], v[112:115], v[172:175], v[116:119]
	v_mfma_f32_16x16x32_bf16 v[108:111], v[140:143], v[172:175], v[108:111]
	v_mfma_f32_16x16x32_bf16 v[96:99], v[112:115], v[180:183], v[96:99]
	v_mfma_f32_16x16x32_bf16 v[88:91], v[140:143], v[180:183], v[88:91]
	v_mfma_f32_16x16x32_bf16 v[80:83], v[112:115], v[188:191], v[80:83]
	v_mfma_f32_16x16x32_bf16 v[72:75], v[140:143], v[188:191], v[72:75]
	s_setprio 0
	s_setprio 1
	v_mfma_f32_16x16x32_bf16 v[124:127], v[144:147], v[160:163], v[124:127]
	v_mfma_f32_16x16x32_bf16 v[120:123], v[152:155], v[160:163], v[120:123]
	v_mfma_f32_16x16x32_bf16 v[100:103], v[144:147], v[168:171], v[100:103]
	v_mfma_f32_16x16x32_bf16 v[92:95], v[152:155], v[168:171], v[92:95]
	v_mfma_f32_16x16x32_bf16 v[84:87], v[144:147], v[176:179], v[84:87]
	v_mfma_f32_16x16x32_bf16 v[76:79], v[152:155], v[176:179], v[76:79]
	v_mfma_f32_16x16x32_bf16 v[68:71], v[144:147], v[184:187], v[68:71]
	v_mfma_f32_16x16x32_bf16 v[64:67], v[152:155], v[184:187], v[64:67]
	v_mfma_f32_16x16x32_bf16 v[124:127], v[148:151], v[164:167], v[124:127]
	v_mfma_f32_16x16x32_bf16 v[120:123], v[156:159], v[164:167], v[120:123]
	v_mfma_f32_16x16x32_bf16 v[100:103], v[148:151], v[172:175], v[100:103]
	v_mfma_f32_16x16x32_bf16 v[92:95], v[156:159], v[172:175], v[92:95]
	v_mfma_f32_16x16x32_bf16 v[84:87], v[148:151], v[180:183], v[84:87]
	v_mfma_f32_16x16x32_bf16 v[76:79], v[156:159], v[180:183], v[76:79]
	v_mfma_f32_16x16x32_bf16 v[68:71], v[148:151], v[188:191], v[68:71]
	v_mfma_f32_16x16x32_bf16 v[64:67], v[156:159], v[188:191], v[64:67]
	s_setprio 0
	s_barrier
; #define PG8_STAGE(bufoff, gbase, voff) do { _Pragma("unroll") for (int _i = 0; _i < 2; ++_i) \
;         __builtin_amdgcn_global_load_lds((const unsigned*)((const char*)(gbase) + (voff)[_i]), (LAS unsigned*)(lds + (bufoff) + ldsw + _i * 8192), 16, 0, 0); } while (0)
; #define PG8_LDA(dst, b, h) do { _Pragma("unroll") for (int m = 0; m < 4; ++m) _Pragma("unroll") for (int k = 0; k < 2; ++k) dst[m][k] = *(const LAS bf16x8*)(lds + PG8_SA(b, h) + aoff + m * 2048 + k * 1024); } while (0)
; #define PG8_MMA(ai, bj, At, Bt) do { __builtin_amdgcn_s_setprio(1); _Pragma("unroll") for (int m = 0; m < 4; ++m) _Pragma("unroll") for (int n = 0; n < 2; ++n) _Pragma("unroll") for (int k = 0; k < 2; ++k) \
;         acc[ai][bj][m][n] = __builtin_amdgcn_mfma_f32_16x16x32_bf16(Bt[n][k], At[m][k], acc[ai][bj][m][n], 0, 0, 0); __builtin_amdgcn_s_setprio(0); } while (0)
; #define PG8_WAIT_V(n) asm volatile("s_waitcnt vmcnt(" #n ")" ::: "memory")
; #define PG8_WAIT_L(n) asm volatile("s_waitcnt lgkmcnt(" #n ")" ::: "memory")
; #define PG8_BAR __builtin_amdgcn_s_barrier()
; #define PG8_SCHED __builtin_amdgcn_sched_barrier(0)
; template <class Epi, class Sched, bool ALIGN_EPI>
; __device__ __forceinline__ void gemm_phase(LAS unsigned char* lds, const Gemm g, const Sched& S, const Epi& E) {
;     ...
;         for (int t = 0; t < nt; t += 2) {
;     ...
;             PG8_LDA(At, 1, 1); PG8_STAGE(PG8_SB(1, 0), b3, voffB); PG8_STAGE(PG8_SB(1, 1), b3 + hstepB, voffB); PG8_STAGE(PG8_SA(1, 0), a3, voffA);
;             PG8_WAIT_V(8); PG8_WAIT_L(0); PG8_BAR; PG8_MMA(1, 0, At, B0); PG8_MMA(1, 1, At, B1); PG8_BAR; PG8_SCHED;
	s_add_i32 s52, s52, s50
	v_lshl_add_u64 v[194:195], v[194:195], 0, s[12:13]
	s_mov_b32 m0, s52
	ds_read_b128 v[160:163], v248 offset:49152
	ds_read_b128 v[164:167], v248 offset:50176
	ds_read_b128 v[168:171], v248 offset:51200
	ds_read_b128 v[172:175], v248 offset:52224
	ds_read_b128 v[176:179], v248 offset:53248
	ds_read_b128 v[180:183], v248 offset:54272
	ds_read_b128 v[184:187], v248 offset:55296
	ds_read_b128 v[188:191], v248 offset:56320
	global_load_lds_dwordx4 v[194:195], off
	s_add_i32 m0, s52, 0x2000
	s_add_u32 s46, s46, 0x100080
	v_lshl_add_u64 v[194:195], v[196:197], 0, s[12:13]
	s_addc_u32 s47, s47, 0
	s_add_i32 s52, s53, s50
	global_load_lds_dwordx4 v[194:195], off
	v_lshl_add_u64 v[194:195], s[46:47], 0, v[216:217]
	s_mov_b32 m0, s52
	s_nop 0
	global_load_lds_dwordx4 v[194:195], off
	v_lshl_add_u64 v[194:195], s[46:47], 0, v[212:213]
	s_add_i32 m0, s52, 0x2000
	s_nop 0
	global_load_lds_dwordx4 v[194:195], off
	v_lshl_add_u64 v[194:195], v[198:199], 0, s[12:13]
	s_mov_b32 m0, s59
	s_nop 0
	global_load_lds_dwordx4 v[194:195], off
	v_lshl_add_u64 v[194:195], v[200:201], 0, s[12:13]
	s_mov_b32 m0, s4
	s_nop 0
	global_load_lds_dwordx4 v[194:195], off
	s_waitcnt vmcnt(8)
	s_waitcnt lgkmcnt(0)
	s_barrier
	s_setprio 1
	s_waitcnt lgkmcnt(0)
	v_mfma_f32_16x16x32_bf16 v[60:63], v[104:107], v[160:163], v[60:63]
	v_mfma_f32_16x16x32_bf16 v[56:59], v[136:139], v[160:163], v[56:59]
	v_mfma_f32_16x16x32_bf16 v[44:47], v[104:107], v[168:171], v[44:47]
	v_mfma_f32_16x16x32_bf16 v[40:43], v[136:139], v[168:171], v[40:43]
	v_mfma_f32_16x16x32_bf16 v[32:35], v[104:107], v[176:179], v[32:35]
	v_mfma_f32_16x16x32_bf16 v[24:27], v[136:139], v[176:179], v[24:27]
	v_mfma_f32_16x16x32_bf16 v[16:19], v[104:107], v[184:187], v[16:19]
	v_mfma_f32_16x16x32_bf16 v[8:11], v[136:139], v[184:187], v[8:11]
	v_mfma_f32_16x16x32_bf16 v[60:63], v[112:115], v[164:167], v[60:63]
	v_mfma_f32_16x16x32_bf16 v[56:59], v[140:143], v[164:167], v[56:59]
	v_mfma_f32_16x16x32_bf16 v[44:47], v[112:115], v[172:175], v[44:47]
	v_mfma_f32_16x16x32_bf16 v[40:43], v[140:143], v[172:175], v[40:43]
	v_mfma_f32_16x16x32_bf16 v[32:35], v[112:115], v[180:183], v[32:35]
	v_mfma_f32_16x16x32_bf16 v[24:27], v[140:143], v[180:183], v[24:27]
	v_mfma_f32_16x16x32_bf16 v[16:19], v[112:115], v[188:191], v[16:19]
	v_mfma_f32_16x16x32_bf16 v[8:11], v[140:143], v[188:191], v[8:11]
	s_setprio 0
	s_setprio 1
	v_mfma_f32_16x16x32_bf16 v[52:55], v[144:147], v[160:163], v[52:55]
	v_mfma_f32_16x16x32_bf16 v[48:51], v[152:155], v[160:163], v[48:51]
	v_mfma_f32_16x16x32_bf16 v[36:39], v[144:147], v[168:171], v[36:39]
	v_mfma_f32_16x16x32_bf16 v[28:31], v[152:155], v[168:171], v[28:31]
	v_mfma_f32_16x16x32_bf16 v[20:23], v[144:147], v[176:179], v[20:23]
	v_mfma_f32_16x16x32_bf16 v[12:15], v[152:155], v[176:179], v[12:15]
	v_mfma_f32_16x16x32_bf16 v[4:7], v[144:147], v[184:187], v[4:7]
	v_mfma_f32_16x16x32_bf16 v[0:3], v[152:155], v[184:187], v[0:3]
	v_mfma_f32_16x16x32_bf16 v[52:55], v[148:151], v[164:167], v[52:55]
	v_mfma_f32_16x16x32_bf16 v[48:51], v[156:159], v[164:167], v[48:51]
	v_mfma_f32_16x16x32_bf16 v[36:39], v[148:151], v[172:175], v[36:39]
	v_mfma_f32_16x16x32_bf16 v[28:31], v[156:159], v[172:175], v[28:31]
	v_mfma_f32_16x16x32_bf16 v[20:23], v[148:151], v[180:183], v[20:23]
	v_mfma_f32_16x16x32_bf16 v[12:15], v[156:159], v[180:183], v[12:15]
	v_mfma_f32_16x16x32_bf16 v[4:7], v[148:151], v[188:191], v[4:7]
	v_mfma_f32_16x16x32_bf16 v[0:3], v[156:159], v[188:191], v[0:3]
	s_setprio 0
	s_barrier
	s_add_i32 s92, s92, 2
	s_add_u32 s44, s44, 0x100
	s_addc_u32 s45, s45, 0
	s_add_u32 s65, s65, 0x100
	s_addc_u32 s81, s81, 0
	s_cmp_gt_u32 s92, 61

; #define PG8_STAGE(bufoff, gbase, voff) do { _Pragma("unroll") for (int _i = 0; _i < 2; ++_i) \
;         __builtin_amdgcn_global_load_lds((const unsigned*)((const char*)(gbase) + (voff)[_i]), (LAS unsigned*)(lds + (bufoff) + ldsw + _i * 8192), 16, 0, 0); } while (0)
; #define PG8_LDA(dst, b, h) do { _Pragma("unroll") for (int m = 0; m < 4; ++m) _Pragma("unroll") for (int k = 0; k < 2; ++k) dst[m][k] = *(const LAS bf16x8*)(lds + PG8_SA(b, h) + aoff + m * 2048 + k * 1024); } while (0)
; #define PG8_LDB(dst, b, h) do { _Pragma("unroll") for (int n = 0; n < 2; ++n) _Pragma("unroll") for (int k = 0; k < 2; ++k) dst[n][k] = *(const LAS bf16x8*)(lds + PG8_SB(b, h) + boff + n * 2048 + k * 1024); } while (0)
; #define PG8_MMA(ai, bj, At, Bt) do { __builtin_amdgcn_s_setprio(1); _Pragma("unroll") for (int m = 0; m < 4; ++m) _Pragma("unroll") for (int n = 0; n < 2; ++n) _Pragma("unroll") for (int k = 0; k < 2; ++k) \
;         acc[ai][bj][m][n] = __builtin_amdgcn_mfma_f32_16x16x32_bf16(Bt[n][k], At[m][k], acc[ai][bj][m][n], 0, 0, 0); __builtin_amdgcn_s_setprio(0); } while (0)
; #define PG8_WAIT_V(n) asm volatile("s_waitcnt vmcnt(" #n ")" ::: "memory")
; #define PG8_WAIT_L(n) asm volatile("s_waitcnt lgkmcnt(" #n ")" ::: "memory")
; #define PG8_BAR __builtin_amdgcn_s_barrier()
; #define PG8_SCHED __builtin_amdgcn_sched_barrier(0)
; template <class Epi, class Sched, bool ALIGN_EPI>
; __device__ __forceinline__ void gemm_phase(LAS unsigned char* lds, const Gemm g, const Sched& S, const Epi& E) {
;     ...
;             PG8_LDB(B0, 0, 0); PG8_LDB(B1, 0, 1); PG8_SCHED; PG8_LDA(At, 0, 0); PG8_STAGE(PG8_SA(1, 1), a1 + hstepA, voffA);
;             PG8_WAIT_V(8); PG8_WAIT_L(0); PG8_BAR; PG8_MMA(0, 0, At, B0); PG8_MMA(0, 1, At, B1); PG8_BAR; PG8_SCHED;
;             PG8_LDA(At, 0, 1); PG8_STAGE(PG8_SB(0, 0), b2, voffB); PG8_STAGE(PG8_SB(0, 1), b2 + hstepB, voffB); PG8_STAGE(PG8_SA(0, 0), a2, voffA);
;             PG8_WAIT_V(8); PG8_WAIT_L(0); PG8_BAR; PG8_MMA(1, 0, At, B0); PG8_MMA(1, 1, At, B1); PG8_BAR; PG8_SCHED;
;     ...
;         for (int a = 0; a < 2; ++a)
; #pragma unroll
;             for (int b = 0; b < 2; ++b)
; #pragma unroll
;                 for (int m = 0; m < 4; ++m)
; #pragma unroll
;                     for (int n = 0; n < 2; ++n) acc[a][b][m][n] = (f32x4){0.f, 0.f, 0.f, 0.f};
;         cur = nxt; cA = nA; cB = nB; ++ui;
.LBB0_286:
	s_ashr_i32 s23, s22, 31
	s_lshl_b64 s[38:39], s[22:23], 19
	s_add_u32 s38, s48, s38
	s_addc_u32 s39, s49, s39
	s_and_b64 s[40:41], s[42:43], exec
	s_cselect_b32 s23, s39, s45
	s_cselect_b32 s85, s38, s44
	s_ashr_i32 s21, s20, 31
	s_lshl_b64 s[40:41], s[20:21], 19
	s_add_u32 s40, s50, s40
	s_addc_u32 s41, s51, s41
	s_and_b64 s[54:55], s[42:43], exec
	s_cselect_b32 s21, s41, s47
	s_cselect_b32 s86, s40, s46
	s_add_u32 s44, s44, 0x40080
	s_addc_u32 s45, s45, 0
	s_add_u32 s87, s46, 0x100
	s_addc_u32 s90, s47, 0
	s_mov_b32 s91, -2
	s_add_u32 s46, s44, 0xfffc0080
	s_addc_u32 s47, s45, -1
	s_add_i32 s92, 0, 0x10000
	s_cmp_eq_u32 s91, 12
	s_cselect_b32 s55, s23, s47
	s_cselect_b32 s54, s85, s46
	s_cselect_b32 s47, s21, s90
	s_cselect_b32 s46, s86, s87
	s_add_i32 s4, 0, 0x14000
	v_add_u32_e32 v132, s92, v160
	v_add_u32_e32 v170, s4, v160
	ds_read_b128 v[120:123], v132
	ds_read_b128 v[124:127], v132 offset:1024
	ds_read_b128 v[128:131], v132 offset:2048
	ds_read_b128 v[132:135], v132 offset:3072
	ds_read_b128 v[154:157], v170
	ds_read_b128 v[162:165], v170 offset:1024
	ds_read_b128 v[166:169], v170 offset:2048
	ds_read_b128 v[170:173], v170 offset:3072
	v_lshl_add_u64 v[190:191], s[44:45], 0, v[150:151]
	s_add_i32 m0, s53, 0xc000
	ds_read_b128 v[174:177], v161
	ds_read_b128 v[178:181], v161 offset:1024
	ds_read_b128 v[182:185], v161 offset:2048
	ds_read_b128 v[186:189], v161 offset:3072
	ds_read_b128 v[194:197], v161 offset:4096
	ds_read_b128 v[198:201], v161 offset:5120
	ds_read_b128 v[202:205], v161 offset:6144
	ds_read_b128 v[212:215], v161 offset:7168
	global_load_lds_dwordx4 v[190:191], off
	v_lshl_add_u64 v[190:191], s[44:45], 0, v[152:153]
	s_add_i32 m0, s53, 0xe000
	s_nop 0
	global_load_lds_dwordx4 v[190:191], off
	s_waitcnt vmcnt(8)
	s_waitcnt lgkmcnt(0)
	s_barrier
	s_setprio 1
	s_waitcnt lgkmcnt(0)
	v_mfma_f32_16x16x32_bf16 v[140:143], v[120:123], v[174:177], 0
	v_mfma_f32_16x16x32_bf16 v[136:139], v[128:131], v[174:177], 0
	v_mfma_f32_16x16x32_bf16 v[108:111], v[120:123], v[182:185], 0
	v_mfma_f32_16x16x32_bf16 v[104:107], v[128:131], v[182:185], 0
	v_mfma_f32_16x16x32_bf16 v[92:95], v[120:123], v[194:197], 0
	v_mfma_f32_16x16x32_bf16 v[88:91], v[128:131], v[194:197], 0
	v_mfma_f32_16x16x32_bf16 v[76:79], v[120:123], v[202:205], 0
	v_mfma_f32_16x16x32_bf16 v[72:75], v[128:131], v[202:205], 0
	v_mfma_f32_16x16x32_bf16 v[140:143], v[124:127], v[178:181], v[140:143]
	v_mfma_f32_16x16x32_bf16 v[136:139], v[132:135], v[178:181], v[136:139]
	v_mfma_f32_16x16x32_bf16 v[108:111], v[124:127], v[186:189], v[108:111]
	v_mfma_f32_16x16x32_bf16 v[104:107], v[132:135], v[186:189], v[104:107]
	v_mfma_f32_16x16x32_bf16 v[92:95], v[124:127], v[198:201], v[92:95]
	v_mfma_f32_16x16x32_bf16 v[88:91], v[132:135], v[198:201], v[88:91]
	v_mfma_f32_16x16x32_bf16 v[76:79], v[124:127], v[212:215], v[76:79]
	v_mfma_f32_16x16x32_bf16 v[72:75], v[132:135], v[212:215], v[72:75]
	s_setprio 0
	s_setprio 1
	v_mfma_f32_16x16x32_bf16 v[116:119], v[154:157], v[174:177], 0
	v_mfma_f32_16x16x32_bf16 v[112:115], v[166:169], v[174:177], 0
	v_mfma_f32_16x16x32_bf16 v[100:103], v[154:157], v[182:185], 0
	v_mfma_f32_16x16x32_bf16 v[96:99], v[166:169], v[182:185], 0
	v_mfma_f32_16x16x32_bf16 v[84:87], v[154:157], v[194:197], 0
	v_mfma_f32_16x16x32_bf16 v[80:83], v[166:169], v[194:197], 0
	v_mfma_f32_16x16x32_bf16 v[68:71], v[154:157], v[202:205], 0
	v_mfma_f32_16x16x32_bf16 v[64:67], v[166:169], v[202:205], 0
	v_mfma_f32_16x16x32_bf16 v[116:119], v[162:165], v[178:181], v[116:119]
	v_mfma_f32_16x16x32_bf16 v[112:115], v[170:173], v[178:181], v[112:115]
	v_mfma_f32_16x16x32_bf16 v[100:103], v[162:165], v[186:189], v[100:103]
	v_mfma_f32_16x16x32_bf16 v[96:99], v[170:173], v[186:189], v[96:99]
	v_mfma_f32_16x16x32_bf16 v[84:87], v[162:165], v[198:201], v[84:87]
	v_mfma_f32_16x16x32_bf16 v[80:83], v[170:173], v[198:201], v[80:83]
	v_mfma_f32_16x16x32_bf16 v[68:71], v[162:165], v[212:215], v[68:71]
	v_mfma_f32_16x16x32_bf16 v[64:67], v[170:173], v[212:215], v[64:67]
	s_setprio 0
	s_barrier
	s_add_i32 s5, s92, s52
	v_lshl_add_u64 v[190:191], s[46:47], 0, v[192:193]
	s_mov_b32 m0, s5
	ds_read_b128 v[174:177], v161 offset:16384
	ds_read_b128 v[178:181], v161 offset:17408
	ds_read_b128 v[182:185], v161 offset:18432
	ds_read_b128 v[186:189], v161 offset:19456
	ds_read_b128 v[194:197], v161 offset:20480
	ds_read_b128 v[198:201], v161 offset:21504
	ds_read_b128 v[202:205], v161 offset:22528
	ds_read_b128 v[212:215], v161 offset:23552
	global_load_lds_dwordx4 v[190:191], off
	s_add_i32 m0, s5, 0x2000
	s_add_u32 vcc_lo, s46, 0x40000
	v_lshl_add_u64 v[216:217], s[46:47], 0, v[144:145]
	s_addc_u32 vcc_hi, s47, 0
	s_add_i32 s4, s4, s52
	global_load_lds_dwordx4 v[216:217], off
	v_lshl_add_u64 v[218:219], vcc, 0, v[192:193]
	s_mov_b32 m0, s4
	v_lshl_add_u64 v[220:221], s[54:55], 0, v[146:147]
	global_load_lds_dwordx4 v[218:219], off
	v_lshl_add_u64 v[218:219], vcc, 0, v[144:145]
	s_add_i32 m0, s4, 0x2000
	s_nop 0
	global_load_lds_dwordx4 v[218:219], off
	v_lshl_add_u64 v[218:219], s[54:55], 0, v[148:149]
	s_mov_b32 m0, s53
	s_nop 0
	global_load_lds_dwordx4 v[218:219], off
	s_mov_b32 m0, s56
	s_nop 0
	global_load_lds_dwordx4 v[220:221], off
	s_waitcnt vmcnt(8)
	s_waitcnt lgkmcnt(0)
	s_barrier
; #define PG8_STAGE(bufoff, gbase, voff) do { _Pragma("unroll") for (int _i = 0; _i < 2; ++_i) \
;         __builtin_amdgcn_global_load_lds((const unsigned*)((const char*)(gbase) + (voff)[_i]), (LAS unsigned*)(lds + (bufoff) + ldsw + _i * 8192), 16, 0, 0); } while (0)
; #define PG8_LDA(dst, b, h) do { _Pragma("unroll") for (int m = 0; m < 4; ++m) _Pragma("unroll") for (int k = 0; k < 2; ++k) dst[m][k] = *(const LAS bf16x8*)(lds + PG8_SA(b, h) + aoff + m * 2048 + k * 1024); } while (0)
; #define PG8_LDB(dst, b, h) do { _Pragma("unroll") for (int n = 0; n < 2; ++n) _Pragma("unroll") for (int k = 0; k < 2; ++k) dst[n][k] = *(const LAS bf16x8*)(lds + PG8_SB(b, h) + boff + n * 2048 + k * 1024); } while (0)
; #define PG8_MMA(ai, bj, At, Bt) do { __builtin_amdgcn_s_setprio(1); _Pragma("unroll") for (int m = 0; m < 4; ++m) _Pragma("unroll") for (int n = 0; n < 2; ++n) _Pragma("unroll") for (int k = 0; k < 2; ++k) \
;         acc[ai][bj][m][n] = __builtin_amdgcn_mfma_f32_16x16x32_bf16(Bt[n][k], At[m][k], acc[ai][bj][m][n], 0, 0, 0); __builtin_amdgcn_s_setprio(0); } while (0)
; #define PG8_WAIT_V(n) asm volatile("s_waitcnt vmcnt(" #n ")" ::: "memory")
; #define PG8_WAIT_L(n) asm volatile("s_waitcnt lgkmcnt(" #n ")" ::: "memory")
; #define PG8_BAR __builtin_amdgcn_s_barrier()
; #define PG8_SCHED __builtin_amdgcn_sched_barrier(0)
; template <class Epi, class Sched, bool ALIGN_EPI>
; __device__ __forceinline__ void gemm_phase(LAS unsigned char* lds, const Gemm g, const Sched& S, const Epi& E) {
;     ...
;             PG8_WAIT_V(8); PG8_WAIT_L(0); PG8_BAR; PG8_MMA(1, 0, At, B0); PG8_MMA(1, 1, At, B1); PG8_BAR; PG8_SCHED;
;             PG8_LDB(B0, 1, 0); PG8_LDB(B1, 1, 1); PG8_SCHED; PG8_LDA(At, 1, 0); PG8_STAGE(PG8_SA(0, 1), a2 + hstepA, voffA);
;             PG8_WAIT_V(8); PG8_WAIT_L(0); PG8_BAR; PG8_MMA(0, 0, At, B0); PG8_MMA(0, 1, At, B1); PG8_BAR; PG8_SCHED;
	s_setprio 1
	s_waitcnt lgkmcnt(0)
	v_mfma_f32_16x16x32_bf16 v[60:63], v[120:123], v[174:177], 0
	v_mfma_f32_16x16x32_bf16 v[56:59], v[128:131], v[174:177], 0
	v_mfma_f32_16x16x32_bf16 v[48:51], v[120:123], v[182:185], 0
	v_mfma_f32_16x16x32_bf16 v[40:43], v[128:131], v[182:185], 0
	v_mfma_f32_16x16x32_bf16 v[32:35], v[120:123], v[194:197], 0
	v_mfma_f32_16x16x32_bf16 v[24:27], v[128:131], v[194:197], 0
	v_mfma_f32_16x16x32_bf16 v[16:19], v[120:123], v[202:205], 0
	v_mfma_f32_16x16x32_bf16 v[8:11], v[128:131], v[202:205], 0
	v_mfma_f32_16x16x32_bf16 v[60:63], v[124:127], v[178:181], v[60:63]
	v_mfma_f32_16x16x32_bf16 v[56:59], v[132:135], v[178:181], v[56:59]
	v_mfma_f32_16x16x32_bf16 v[48:51], v[124:127], v[186:189], v[48:51]
	v_mfma_f32_16x16x32_bf16 v[40:43], v[132:135], v[186:189], v[40:43]
	v_mfma_f32_16x16x32_bf16 v[32:35], v[124:127], v[198:201], v[32:35]
	v_mfma_f32_16x16x32_bf16 v[24:27], v[132:135], v[198:201], v[24:27]
	v_mfma_f32_16x16x32_bf16 v[16:19], v[124:127], v[212:215], v[16:19]
	v_mfma_f32_16x16x32_bf16 v[8:11], v[132:135], v[212:215], v[8:11]
	s_setprio 0
	s_setprio 1
	v_mfma_f32_16x16x32_bf16 v[52:55], v[154:157], v[174:177], 0
	v_mfma_f32_16x16x32_bf16 v[44:47], v[166:169], v[174:177], 0
	v_mfma_f32_16x16x32_bf16 v[36:39], v[154:157], v[182:185], 0
	v_mfma_f32_16x16x32_bf16 v[28:31], v[166:169], v[182:185], 0
	v_mfma_f32_16x16x32_bf16 v[20:23], v[154:157], v[194:197], 0
	v_mfma_f32_16x16x32_bf16 v[12:15], v[166:169], v[194:197], 0
	v_mfma_f32_16x16x32_bf16 v[4:7], v[154:157], v[202:205], 0
	v_mfma_f32_16x16x32_bf16 v[0:3], v[166:169], v[202:205], 0
	v_mfma_f32_16x16x32_bf16 v[52:55], v[162:165], v[178:181], v[52:55]
	v_mfma_f32_16x16x32_bf16 v[44:47], v[170:173], v[178:181], v[44:47]
	v_mfma_f32_16x16x32_bf16 v[36:39], v[162:165], v[186:189], v[36:39]
	v_mfma_f32_16x16x32_bf16 v[28:31], v[170:173], v[186:189], v[28:31]
	v_mfma_f32_16x16x32_bf16 v[20:23], v[162:165], v[198:201], v[20:23]
	v_mfma_f32_16x16x32_bf16 v[12:15], v[170:173], v[198:201], v[12:15]
	v_mfma_f32_16x16x32_bf16 v[4:7], v[162:165], v[212:215], v[4:7]
	v_mfma_f32_16x16x32_bf16 v[0:3], v[170:173], v[212:215], v[0:3]
	s_setprio 0
	s_barrier
	s_add_i32 s4, 0, 0x18000
	s_add_i32 s5, 0, 0x1c000
	v_add_u32_e32 v132, s4, v160
	v_add_u32_e32 v170, s5, v160
	ds_read_b128 v[120:123], v132
	ds_read_b128 v[124:127], v132 offset:1024
	ds_read_b128 v[128:131], v132 offset:2048
	ds_read_b128 v[132:135], v132 offset:3072
	ds_read_b128 v[154:157], v170
	ds_read_b128 v[162:165], v170 offset:1024
	ds_read_b128 v[166:169], v170 offset:2048
	ds_read_b128 v[170:173], v170 offset:3072
	s_add_u32 s54, s54, 0x40000
	s_addc_u32 s55, s55, 0
	s_mov_b32 m0, s57
	v_lshl_add_u64 v[222:223], s[54:55], 0, v[148:149]
	ds_read_b128 v[174:177], v161 offset:32768
	ds_read_b128 v[178:181], v161 offset:33792
	ds_read_b128 v[182:185], v161 offset:34816
	ds_read_b128 v[186:189], v161 offset:35840
	ds_read_b128 v[194:197], v161 offset:36864
	ds_read_b128 v[198:201], v161 offset:37888
	ds_read_b128 v[202:205], v161 offset:38912
	ds_read_b128 v[212:215], v161 offset:39936
	global_load_lds_dwordx4 v[222:223], off
	v_lshl_add_u64 v[222:223], s[54:55], 0, v[146:147]
	s_mov_b32 m0, s58
	s_nop 0
	global_load_lds_dwordx4 v[222:223], off
	s_waitcnt vmcnt(8)
	s_waitcnt lgkmcnt(0)
	s_barrier
	s_setprio 1
	s_waitcnt lgkmcnt(0)
	v_mfma_f32_16x16x32_bf16 v[140:143], v[120:123], v[174:177], v[140:143]
	v_mfma_f32_16x16x32_bf16 v[136:139], v[128:131], v[174:177], v[136:139]
	v_mfma_f32_16x16x32_bf16 v[108:111], v[120:123], v[182:185], v[108:111]
	v_mfma_f32_16x16x32_bf16 v[104:107], v[128:131], v[182:185], v[104:107]
	v_mfma_f32_16x16x32_bf16 v[92:95], v[120:123], v[194:197], v[92:95]
	v_mfma_f32_16x16x32_bf16 v[88:91], v[128:131], v[194:197], v[88:91]
	v_mfma_f32_16x16x32_bf16 v[76:79], v[120:123], v[202:205], v[76:79]
	v_mfma_f32_16x16x32_bf16 v[72:75], v[128:131], v[202:205], v[72:75]
	v_mfma_f32_16x16x32_bf16 v[140:143], v[124:127], v[178:181], v[140:143]
	v_mfma_f32_16x16x32_bf16 v[136:139], v[132:135], v[178:181], v[136:139]
	v_mfma_f32_16x16x32_bf16 v[108:111], v[124:127], v[186:189], v[108:111]
	v_mfma_f32_16x16x32_bf16 v[104:107], v[132:135], v[186:189], v[104:107]
	v_mfma_f32_16x16x32_bf16 v[92:95], v[124:127], v[198:201], v[92:95]
	v_mfma_f32_16x16x32_bf16 v[88:91], v[132:135], v[198:201], v[88:91]
	v_mfma_f32_16x16x32_bf16 v[76:79], v[124:127], v[212:215], v[76:79]
	v_mfma_f32_16x16x32_bf16 v[72:75], v[132:135], v[212:215], v[72:75]
	s_setprio 0
	s_setprio 1
	v_mfma_f32_16x16x32_bf16 v[116:119], v[154:157], v[174:177], v[116:119]
	v_mfma_f32_16x16x32_bf16 v[112:115], v[166:169], v[174:177], v[112:115]
	v_mfma_f32_16x16x32_bf16 v[100:103], v[154:157], v[182:185], v[100:103]
	v_mfma_f32_16x16x32_bf16 v[96:99], v[166:169], v[182:185], v[96:99]
	v_mfma_f32_16x16x32_bf16 v[84:87], v[154:157], v[194:197], v[84:87]
	v_mfma_f32_16x16x32_bf16 v[80:83], v[166:169], v[194:197], v[80:83]
	v_mfma_f32_16x16x32_bf16 v[68:71], v[154:157], v[202:205], v[68:71]
	v_mfma_f32_16x16x32_bf16 v[64:67], v[166:169], v[202:205], v[64:67]
	v_mfma_f32_16x16x32_bf16 v[116:119], v[162:165], v[178:181], v[116:119]
	v_mfma_f32_16x16x32_bf16 v[112:115], v[170:173], v[178:181], v[112:115]
	v_mfma_f32_16x16x32_bf16 v[100:103], v[162:165], v[186:189], v[100:103]
	v_mfma_f32_16x16x32_bf16 v[96:99], v[170:173], v[186:189], v[96:99]
	v_mfma_f32_16x16x32_bf16 v[84:87], v[162:165], v[198:201], v[84:87]
	v_mfma_f32_16x16x32_bf16 v[80:83], v[170:173], v[198:201], v[80:83]
	v_mfma_f32_16x16x32_bf16 v[68:71], v[162:165], v[212:215], v[68:71]
	v_mfma_f32_16x16x32_bf16 v[64:67], v[170:173], v[212:215], v[64:67]
	s_setprio 0
	s_barrier
; #define PG8_STAGE(bufoff, gbase, voff) do { _Pragma("unroll") for (int _i = 0; _i < 2; ++_i) \
;         __builtin_amdgcn_global_load_lds((const unsigned*)((const char*)(gbase) + (voff)[_i]), (LAS unsigned*)(lds + (bufoff) + ldsw + _i * 8192), 16, 0, 0); } while (0)
; #define PG8_LDA(dst, b, h) do { _Pragma("unroll") for (int m = 0; m < 4; ++m) _Pragma("unroll") for (int k = 0; k < 2; ++k) dst[m][k] = *(const LAS bf16x8*)(lds + PG8_SA(b, h) + aoff + m * 2048 + k * 1024); } while (0)
; #define PG8_MMA(ai, bj, At, Bt) do { __builtin_amdgcn_s_setprio(1); _Pragma("unroll") for (int m = 0; m < 4; ++m) _Pragma("unroll") for (int n = 0; n < 2; ++n) _Pragma("unroll") for (int k = 0; k < 2; ++k) \
;         acc[ai][bj][m][n] = __builtin_amdgcn_mfma_f32_16x16x32_bf16(Bt[n][k], At[m][k], acc[ai][bj][m][n], 0, 0, 0); __builtin_amdgcn_s_setprio(0); } while (0)
; #define PG8_WAIT_V(n) asm volatile("s_waitcnt vmcnt(" #n ")" ::: "memory")
; #define PG8_WAIT_L(n) asm volatile("s_waitcnt lgkmcnt(" #n ")" ::: "memory")
; #define PG8_BAR __builtin_amdgcn_s_barrier()
; #define PG8_SCHED __builtin_amdgcn_sched_barrier(0)
; template <class Epi, class Sched, bool ALIGN_EPI>
; __device__ __forceinline__ void gemm_phase(LAS unsigned char* lds, const Gemm g, const Sched& S, const Epi& E) {
;     ...
;         for (int t = 0; t < nt; t += 2) {
;     ...
;             PG8_LDA(At, 1, 1); PG8_STAGE(PG8_SB(1, 0), b3, voffB); PG8_STAGE(PG8_SB(1, 1), b3 + hstepB, voffB); PG8_STAGE(PG8_SA(1, 0), a3, voffA);
;             PG8_WAIT_V(8); PG8_WAIT_L(0); PG8_BAR; PG8_MMA(1, 0, At, B0); PG8_MMA(1, 1, At, B1); PG8_BAR; PG8_SCHED;
	s_add_i32 s4, s4, s52
	v_lshl_add_u64 v[190:191], v[190:191], 0, s[12:13]
	s_mov_b32 m0, s4
	ds_read_b128 v[174:177], v161 offset:49152
	ds_read_b128 v[178:181], v161 offset:50176
	ds_read_b128 v[182:185], v161 offset:51200
	ds_read_b128 v[186:189], v161 offset:52224
	ds_read_b128 v[194:197], v161 offset:53248
	ds_read_b128 v[198:201], v161 offset:54272
	ds_read_b128 v[202:205], v161 offset:55296
	ds_read_b128 v[212:215], v161 offset:56320
	global_load_lds_dwordx4 v[190:191], off
	s_add_i32 m0, s4, 0x2000
	s_add_u32 s46, s46, 0x40080
	v_lshl_add_u64 v[190:191], v[216:217], 0, s[12:13]
	s_addc_u32 s47, s47, 0
	s_add_i32 s4, s5, s52
	global_load_lds_dwordx4 v[190:191], off
	v_lshl_add_u64 v[190:191], s[46:47], 0, v[192:193]
	s_mov_b32 m0, s4
	s_nop 0
	global_load_lds_dwordx4 v[190:191], off
	v_lshl_add_u64 v[190:191], s[46:47], 0, v[144:145]
	s_add_i32 m0, s4, 0x2000
	s_nop 0
	global_load_lds_dwordx4 v[190:191], off
	v_lshl_add_u64 v[190:191], v[218:219], 0, s[12:13]
	s_mov_b32 m0, s65
	s_nop 0
	global_load_lds_dwordx4 v[190:191], off
	v_lshl_add_u64 v[190:191], v[220:221], 0, s[12:13]
	s_mov_b32 m0, s66
	s_nop 0
	global_load_lds_dwordx4 v[190:191], off
	s_waitcnt vmcnt(8)
	s_waitcnt lgkmcnt(0)
	s_barrier
	s_setprio 1
	s_waitcnt lgkmcnt(0)
	v_mfma_f32_16x16x32_bf16 v[60:63], v[120:123], v[174:177], v[60:63]
	v_mfma_f32_16x16x32_bf16 v[56:59], v[128:131], v[174:177], v[56:59]
	v_mfma_f32_16x16x32_bf16 v[48:51], v[120:123], v[182:185], v[48:51]
	v_mfma_f32_16x16x32_bf16 v[40:43], v[128:131], v[182:185], v[40:43]
	v_mfma_f32_16x16x32_bf16 v[32:35], v[120:123], v[194:197], v[32:35]
	v_mfma_f32_16x16x32_bf16 v[24:27], v[128:131], v[194:197], v[24:27]
	v_mfma_f32_16x16x32_bf16 v[16:19], v[120:123], v[202:205], v[16:19]
	v_mfma_f32_16x16x32_bf16 v[8:11], v[128:131], v[202:205], v[8:11]
	v_mfma_f32_16x16x32_bf16 v[60:63], v[124:127], v[178:181], v[60:63]
	v_mfma_f32_16x16x32_bf16 v[56:59], v[132:135], v[178:181], v[56:59]
	v_mfma_f32_16x16x32_bf16 v[48:51], v[124:127], v[186:189], v[48:51]
	v_mfma_f32_16x16x32_bf16 v[40:43], v[132:135], v[186:189], v[40:43]
	v_mfma_f32_16x16x32_bf16 v[32:35], v[124:127], v[198:201], v[32:35]
	v_mfma_f32_16x16x32_bf16 v[24:27], v[132:135], v[198:201], v[24:27]
	v_mfma_f32_16x16x32_bf16 v[16:19], v[124:127], v[212:215], v[16:19]
	v_mfma_f32_16x16x32_bf16 v[8:11], v[132:135], v[212:215], v[8:11]
	s_setprio 0
	s_setprio 1
	v_mfma_f32_16x16x32_bf16 v[52:55], v[154:157], v[174:177], v[52:55]
	v_mfma_f32_16x16x32_bf16 v[44:47], v[166:169], v[174:177], v[44:47]
	v_mfma_f32_16x16x32_bf16 v[36:39], v[154:157], v[182:185], v[36:39]
	v_mfma_f32_16x16x32_bf16 v[28:31], v[166:169], v[182:185], v[28:31]
	v_mfma_f32_16x16x32_bf16 v[20:23], v[154:157], v[194:197], v[20:23]
	v_mfma_f32_16x16x32_bf16 v[12:15], v[166:169], v[194:197], v[12:15]
	v_mfma_f32_16x16x32_bf16 v[4:7], v[154:157], v[202:205], v[4:7]
	v_mfma_f32_16x16x32_bf16 v[0:3], v[166:169], v[202:205], v[0:3]
	v_mfma_f32_16x16x32_bf16 v[52:55], v[162:165], v[178:181], v[52:55]
	v_mfma_f32_16x16x32_bf16 v[44:47], v[170:173], v[178:181], v[44:47]
	v_mfma_f32_16x16x32_bf16 v[36:39], v[162:165], v[186:189], v[36:39]
	v_mfma_f32_16x16x32_bf16 v[28:31], v[170:173], v[186:189], v[28:31]
	v_mfma_f32_16x16x32_bf16 v[20:23], v[162:165], v[198:201], v[20:23]
	v_mfma_f32_16x16x32_bf16 v[12:15], v[170:173], v[198:201], v[12:15]
	v_mfma_f32_16x16x32_bf16 v[4:7], v[162:165], v[212:215], v[4:7]
	v_mfma_f32_16x16x32_bf16 v[0:3], v[170:173], v[212:215], v[0:3]
	s_setprio 0
	s_barrier
	s_add_i32 s91, s91, 2
	s_add_u32 s44, s44, 0x100
	s_addc_u32 s45, s45, 0
	s_add_u32 s87, s87, 0x100
	s_addc_u32 s90, s90, 0
	s_cmp_gt_u32 s91, 13

; #define PG8_STAGE(bufoff, gbase, voff) do { _Pragma("unroll") for (int _i = 0; _i < 2; ++_i) \
;         __builtin_amdgcn_global_load_lds((const unsigned*)((const char*)(gbase) + (voff)[_i]), (LAS unsigned*)(lds + (bufoff) + ldsw + _i * 8192), 16, 0, 0); } while (0)
; #define PG8_LDA(dst, b, h) do { _Pragma("unroll") for (int m = 0; m < 4; ++m) _Pragma("unroll") for (int k = 0; k < 2; ++k) dst[m][k] = *(const LAS bf16x8*)(lds + PG8_SA(b, h) + aoff + m * 2048 + k * 1024); } while (0)
; #define PG8_LDB(dst, b, h) do { _Pragma("unroll") for (int n = 0; n < 2; ++n) _Pragma("unroll") for (int k = 0; k < 2; ++k) dst[n][k] = *(const LAS bf16x8*)(lds + PG8_SB(b, h) + boff + n * 2048 + k * 1024); } while (0)
; #define PG8_MMA(ai, bj, At, Bt) do { __builtin_amdgcn_s_setprio(1); _Pragma("unroll") for (int m = 0; m < 4; ++m) _Pragma("unroll") for (int n = 0; n < 2; ++n) _Pragma("unroll") for (int k = 0; k < 2; ++k) \
;         acc[ai][bj][m][n] = __builtin_amdgcn_mfma_f32_16x16x32_bf16(Bt[n][k], At[m][k], acc[ai][bj][m][n], 0, 0, 0); __builtin_amdgcn_s_setprio(0); } while (0)
; #define PG8_WAIT_V(n) asm volatile("s_waitcnt vmcnt(" #n ")" ::: "memory")
; #define PG8_WAIT_L(n) asm volatile("s_waitcnt lgkmcnt(" #n ")" ::: "memory")
; #define PG8_BAR __builtin_amdgcn_s_barrier()
; #define PG8_SCHED __builtin_amdgcn_sched_barrier(0)
; template <class Epi, class Sched, bool ALIGN_EPI>
; __device__ __forceinline__ void gemm_phase(LAS unsigned char* lds, const Gemm g, const Sched& S, const Epi& E) {
;     ...
;             PG8_LDB(B0, 0, 0); PG8_LDB(B1, 0, 1); PG8_SCHED; PG8_LDA(At, 0, 0); PG8_STAGE(PG8_SA(1, 1), a1 + hstepA, voffA);
;             PG8_WAIT_V(8); PG8_WAIT_L(0); PG8_BAR; PG8_MMA(0, 0, At, B0); PG8_MMA(0, 1, At, B1); PG8_BAR; PG8_SCHED;
;             PG8_LDA(At, 0, 1); PG8_STAGE(PG8_SB(0, 0), b2, voffB); PG8_STAGE(PG8_SB(0, 1), b2 + hstepB, voffB); PG8_STAGE(PG8_SA(0, 0), a2, voffA);
;             PG8_WAIT_V(8); PG8_WAIT_L(0); PG8_BAR; PG8_MMA(1, 0, At, B0); PG8_MMA(1, 1, At, B1); PG8_BAR; PG8_SCHED;
;     ...
;         for (int a = 0; a < 2; ++a)
; #pragma unroll
;             for (int b = 0; b < 2; ++b)
; #pragma unroll
;                 for (int m = 0; m < 4; ++m)
; #pragma unroll
;                     for (int n = 0; n < 2; ++n) acc[a][b][m][n] = (f32x4){0.f, 0.f, 0.f, 0.f};
;         cur = nxt; cA = nA; cB = nB; ++ui;
.LBB0_387:
	s_add_i32 s77, s77, 1
	s_mov_b64 s[44:45], s[6:7]
	s_lshr_b32 s6, s77, 1
	s_mul_i32 s6, s6, s85
	s_mov_b32 s42, s80
	s_mov_b32 s84, s80
	s_add_i32 s80, s6, s2
	s_cmpk_lt_i32 s80, 0x100
	s_mov_b32 s43, s76
	s_mov_b32 s81, s76
	s_cselect_b64 s[48:49], -1, 0
	s_and_b32 s76, s77, 1
	s_and_b64 s[6:7], s[48:49], exec
	s_cselect_b32 s6, s80, s42
	s_mov_b64 s[54:55], s[46:47]
	s_cselect_b32 s46, s76, s43
	s_ashr_i32 s7, s6, 31
	s_lshl_b64 s[6:7], s[6:7], 18
	s_add_u32 s6, s50, s6
	s_addc_u32 s7, s51, s7
	s_and_b64 s[56:57], s[48:49], exec
	s_cselect_b32 s85, s7, s45
	s_cselect_b32 s86, s6, s44
	s_ashr_i32 s47, s46, 31
	s_lshl_b64 s[46:47], s[46:47], 18
	s_add_u32 s46, s4, s46
	s_addc_u32 s47, s5, s47
	s_and_b64 s[56:57], s[48:49], exec
	s_cselect_b32 s87, s47, s55
	s_cselect_b32 s90, s46, s54
	s_add_u32 s44, s44, 0x20080
	s_addc_u32 s45, s45, 0
	s_add_u32 s91, s54, 0x100
	s_addc_u32 s92, s55, 0
	s_mov_b32 vcc_lo, -2
	s_waitcnt lgkmcnt(0)
	s_add_u32 s42, s44, 0xfffe0080
	s_addc_u32 s43, s45, -1
	s_add_i32 vcc_hi, 0, 0x10000
	s_cmp_eq_u32 vcc_lo, 4
	s_cselect_b32 s57, s85, s43
	s_cselect_b32 s56, s86, s42
	s_cselect_b32 s55, s87, s92
	s_cselect_b32 s54, s90, s91
	s_add_i32 s8, 0, 0x14000
	v_add_u32_e32 v140, vcc_hi, v184
	v_add_u32_e32 v156, s8, v184
	ds_read_b128 v[72:75], v140
	ds_read_b128 v[76:79], v140 offset:1024
	ds_read_b128 v[136:139], v140 offset:2048
	ds_read_b128 v[140:143], v140 offset:3072
	ds_read_b128 v[144:147], v156
	ds_read_b128 v[148:151], v156 offset:1024
	ds_read_b128 v[152:155], v156 offset:2048
	ds_read_b128 v[156:159], v156 offset:3072
	v_lshl_add_u64 v[190:191], s[44:45], 0, v[166:167]
	s_add_i32 m0, s53, 0xc000
	ds_read_b128 v[170:173], v185
	ds_read_b128 v[174:177], v185 offset:1024
	ds_read_b128 v[178:181], v185 offset:2048
	ds_read_b128 v[186:189], v185 offset:3072
	ds_read_b128 v[194:197], v185 offset:4096
	ds_read_b128 v[198:201], v185 offset:5120
	ds_read_b128 v[202:205], v185 offset:6144
	ds_read_b128 v[212:215], v185 offset:7168
	global_load_lds_dwordx4 v[190:191], off
	v_lshl_add_u64 v[190:191], s[44:45], 0, v[168:169]
	s_add_i32 m0, s53, 0xe000
	s_nop 0
	global_load_lds_dwordx4 v[190:191], off
	s_waitcnt vmcnt(8)
	s_waitcnt lgkmcnt(0)
	s_barrier
	s_setprio 1
	s_waitcnt lgkmcnt(0)
	v_mfma_f32_16x16x32_bf16 v[64:67], v[72:75], v[170:173], 0
	v_mfma_f32_16x16x32_bf16 v[60:63], v[136:139], v[170:173], 0
	v_mfma_f32_16x16x32_bf16 v[124:127], v[72:75], v[178:181], 0
	v_mfma_f32_16x16x32_bf16 v[120:123], v[136:139], v[178:181], 0
	v_mfma_f32_16x16x32_bf16 v[108:111], v[72:75], v[194:197], 0
	v_mfma_f32_16x16x32_bf16 v[104:107], v[136:139], v[194:197], 0
	v_mfma_f32_16x16x32_bf16 v[92:95], v[72:75], v[202:205], 0
	v_mfma_f32_16x16x32_bf16 v[88:91], v[136:139], v[202:205], 0
	v_mfma_f32_16x16x32_bf16 v[64:67], v[76:79], v[174:177], v[64:67]
	v_mfma_f32_16x16x32_bf16 v[60:63], v[140:143], v[174:177], v[60:63]
	v_mfma_f32_16x16x32_bf16 v[124:127], v[76:79], v[186:189], v[124:127]
	v_mfma_f32_16x16x32_bf16 v[120:123], v[140:143], v[186:189], v[120:123]
	v_mfma_f32_16x16x32_bf16 v[108:111], v[76:79], v[198:201], v[108:111]
	v_mfma_f32_16x16x32_bf16 v[104:107], v[140:143], v[198:201], v[104:107]
	v_mfma_f32_16x16x32_bf16 v[92:95], v[76:79], v[212:215], v[92:95]
	v_mfma_f32_16x16x32_bf16 v[88:91], v[140:143], v[212:215], v[88:91]
	s_setprio 0
	s_setprio 1
	v_mfma_f32_16x16x32_bf16 v[132:135], v[144:147], v[170:173], 0
	v_mfma_f32_16x16x32_bf16 v[128:131], v[152:155], v[170:173], 0
	v_mfma_f32_16x16x32_bf16 v[116:119], v[144:147], v[178:181], 0
	v_mfma_f32_16x16x32_bf16 v[112:115], v[152:155], v[178:181], 0
	v_mfma_f32_16x16x32_bf16 v[100:103], v[144:147], v[194:197], 0
	v_mfma_f32_16x16x32_bf16 v[96:99], v[152:155], v[194:197], 0
	v_mfma_f32_16x16x32_bf16 v[84:87], v[144:147], v[202:205], 0
	v_mfma_f32_16x16x32_bf16 v[80:83], v[152:155], v[202:205], 0
	v_mfma_f32_16x16x32_bf16 v[132:135], v[148:151], v[174:177], v[132:135]
	v_mfma_f32_16x16x32_bf16 v[128:131], v[156:159], v[174:177], v[128:131]
	v_mfma_f32_16x16x32_bf16 v[116:119], v[148:151], v[186:189], v[116:119]
	v_mfma_f32_16x16x32_bf16 v[112:115], v[156:159], v[186:189], v[112:115]
	v_mfma_f32_16x16x32_bf16 v[100:103], v[148:151], v[198:201], v[100:103]
	v_mfma_f32_16x16x32_bf16 v[96:99], v[156:159], v[198:201], v[96:99]
	v_mfma_f32_16x16x32_bf16 v[84:87], v[148:151], v[212:215], v[84:87]
	v_mfma_f32_16x16x32_bf16 v[80:83], v[156:159], v[212:215], v[80:83]
	s_setprio 0
	s_barrier
	s_add_i32 s9, vcc_hi, s52
	v_lshl_add_u64 v[190:191], s[54:55], 0, v[192:193]
	s_mov_b32 m0, s9
	ds_read_b128 v[170:173], v185 offset:16384
	ds_read_b128 v[174:177], v185 offset:17408
	ds_read_b128 v[178:181], v185 offset:18432
	ds_read_b128 v[186:189], v185 offset:19456
	ds_read_b128 v[194:197], v185 offset:20480
	ds_read_b128 v[198:201], v185 offset:21504
	ds_read_b128 v[202:205], v185 offset:22528
	ds_read_b128 v[212:215], v185 offset:23552
	global_load_lds_dwordx4 v[190:191], off
	s_add_i32 m0, s9, 0x2000
	s_add_u32 s42, s54, 0x20000
	v_lshl_add_u64 v[216:217], s[54:55], 0, v[160:161]
	s_addc_u32 s43, s55, 0
	s_add_i32 s8, s8, s52
	global_load_lds_dwordx4 v[216:217], off
	v_lshl_add_u64 v[218:219], s[42:43], 0, v[192:193]
	s_mov_b32 m0, s8
	v_lshl_add_u64 v[220:221], s[56:57], 0, v[162:163]
	global_load_lds_dwordx4 v[218:219], off
	v_lshl_add_u64 v[218:219], s[42:43], 0, v[160:161]
	s_add_i32 m0, s8, 0x2000
	s_nop 0
	global_load_lds_dwordx4 v[218:219], off
	v_lshl_add_u64 v[218:219], s[56:57], 0, v[164:165]
	s_mov_b32 m0, s53
	s_nop 0
	global_load_lds_dwordx4 v[218:219], off
	s_mov_b32 m0, s58
	s_nop 0
	global_load_lds_dwordx4 v[220:221], off
	s_waitcnt vmcnt(8)
	s_waitcnt lgkmcnt(0)
	s_barrier
; #define PG8_STAGE(bufoff, gbase, voff) do { _Pragma("unroll") for (int _i = 0; _i < 2; ++_i) \
;         __builtin_amdgcn_global_load_lds((const unsigned*)((const char*)(gbase) + (voff)[_i]), (LAS unsigned*)(lds + (bufoff) + ldsw + _i * 8192), 16, 0, 0); } while (0)
; #define PG8_LDA(dst, b, h) do { _Pragma("unroll") for (int m = 0; m < 4; ++m) _Pragma("unroll") for (int k = 0; k < 2; ++k) dst[m][k] = *(const LAS bf16x8*)(lds + PG8_SA(b, h) + aoff + m * 2048 + k * 1024); } while (0)
; #define PG8_LDB(dst, b, h) do { _Pragma("unroll") for (int n = 0; n < 2; ++n) _Pragma("unroll") for (int k = 0; k < 2; ++k) dst[n][k] = *(const LAS bf16x8*)(lds + PG8_SB(b, h) + boff + n * 2048 + k * 1024); } while (0)
; #define PG8_MMA(ai, bj, At, Bt) do { __builtin_amdgcn_s_setprio(1); _Pragma("unroll") for (int m = 0; m < 4; ++m) _Pragma("unroll") for (int n = 0; n < 2; ++n) _Pragma("unroll") for (int k = 0; k < 2; ++k) \
;         acc[ai][bj][m][n] = __builtin_amdgcn_mfma_f32_16x16x32_bf16(Bt[n][k], At[m][k], acc[ai][bj][m][n], 0, 0, 0); __builtin_amdgcn_s_setprio(0); } while (0)
; #define PG8_WAIT_V(n) asm volatile("s_waitcnt vmcnt(" #n ")" ::: "memory")
; #define PG8_WAIT_L(n) asm volatile("s_waitcnt lgkmcnt(" #n ")" ::: "memory")
; #define PG8_BAR __builtin_amdgcn_s_barrier()
; #define PG8_SCHED __builtin_amdgcn_sched_barrier(0)
; template <class Epi, class Sched, bool ALIGN_EPI>
; __device__ __forceinline__ void gemm_phase(LAS unsigned char* lds, const Gemm g, const Sched& S, const Epi& E) {
;     ...
;             PG8_WAIT_V(8); PG8_WAIT_L(0); PG8_BAR; PG8_MMA(0, 0, At, B0); PG8_MMA(0, 1, At, B1); PG8_BAR; PG8_SCHED;
;             PG8_LDA(At, 0, 1); PG8_STAGE(PG8_SB(0, 0), b2, voffB); PG8_STAGE(PG8_SB(0, 1), b2 + hstepB, voffB); PG8_STAGE(PG8_SA(0, 0), a2, voffA);
;             PG8_WAIT_V(8); PG8_WAIT_L(0); PG8_BAR; PG8_MMA(1, 0, At, B0); PG8_MMA(1, 1, At, B1); PG8_BAR; PG8_SCHED;
;             PG8_LDB(B0, 1, 0); PG8_LDB(B1, 1, 1); PG8_SCHED; PG8_LDA(At, 1, 0); PG8_STAGE(PG8_SA(0, 1), a2 + hstepA, voffA);
;             PG8_WAIT_V(8); PG8_WAIT_L(0); PG8_BAR; PG8_MMA(0, 0, At, B0); PG8_MMA(0, 1, At, B1); PG8_BAR; PG8_SCHED;
	s_setprio 1
	s_waitcnt lgkmcnt(0)
	v_mfma_f32_16x16x32_bf16 v[68:71], v[72:75], v[170:173], 0
	v_mfma_f32_16x16x32_bf16 v[56:59], v[136:139], v[170:173], 0
	v_mfma_f32_16x16x32_bf16 v[44:47], v[72:75], v[178:181], 0
	v_mfma_f32_16x16x32_bf16 v[40:43], v[136:139], v[178:181], 0
	v_mfma_f32_16x16x32_bf16 v[28:31], v[72:75], v[194:197], 0
	v_mfma_f32_16x16x32_bf16 v[24:27], v[136:139], v[194:197], 0
	v_mfma_f32_16x16x32_bf16 v[12:15], v[72:75], v[202:205], 0
	v_mfma_f32_16x16x32_bf16 v[8:11], v[136:139], v[202:205], 0
	v_mfma_f32_16x16x32_bf16 v[68:71], v[76:79], v[174:177], v[68:71]
	v_mfma_f32_16x16x32_bf16 v[56:59], v[140:143], v[174:177], v[56:59]
	v_mfma_f32_16x16x32_bf16 v[44:47], v[76:79], v[186:189], v[44:47]
	v_mfma_f32_16x16x32_bf16 v[40:43], v[140:143], v[186:189], v[40:43]
	v_mfma_f32_16x16x32_bf16 v[28:31], v[76:79], v[198:201], v[28:31]
	v_mfma_f32_16x16x32_bf16 v[24:27], v[140:143], v[198:201], v[24:27]
	v_mfma_f32_16x16x32_bf16 v[12:15], v[76:79], v[212:215], v[12:15]
	v_mfma_f32_16x16x32_bf16 v[8:11], v[140:143], v[212:215], v[8:11]
	s_setprio 0
	s_setprio 1
	v_mfma_f32_16x16x32_bf16 v[52:55], v[144:147], v[170:173], 0
	v_mfma_f32_16x16x32_bf16 v[48:51], v[152:155], v[170:173], 0
	v_mfma_f32_16x16x32_bf16 v[36:39], v[144:147], v[178:181], 0
	v_mfma_f32_16x16x32_bf16 v[32:35], v[152:155], v[178:181], 0
	v_mfma_f32_16x16x32_bf16 v[20:23], v[144:147], v[194:197], 0
	v_mfma_f32_16x16x32_bf16 v[16:19], v[152:155], v[194:197], 0
	v_mfma_f32_16x16x32_bf16 v[4:7], v[144:147], v[202:205], 0
	v_mfma_f32_16x16x32_bf16 v[0:3], v[152:155], v[202:205], 0
	v_mfma_f32_16x16x32_bf16 v[52:55], v[148:151], v[174:177], v[52:55]
	v_mfma_f32_16x16x32_bf16 v[48:51], v[156:159], v[174:177], v[48:51]
	v_mfma_f32_16x16x32_bf16 v[36:39], v[148:151], v[186:189], v[36:39]
	v_mfma_f32_16x16x32_bf16 v[32:35], v[156:159], v[186:189], v[32:35]
	v_mfma_f32_16x16x32_bf16 v[20:23], v[148:151], v[198:201], v[20:23]
	v_mfma_f32_16x16x32_bf16 v[16:19], v[156:159], v[198:201], v[16:19]
	v_mfma_f32_16x16x32_bf16 v[4:7], v[148:151], v[212:215], v[4:7]
	v_mfma_f32_16x16x32_bf16 v[0:3], v[156:159], v[212:215], v[0:3]
	s_setprio 0
	s_barrier
	s_add_i32 s8, 0, 0x18000
	s_add_i32 s9, 0, 0x1c000
	v_add_u32_e32 v140, s8, v184
	v_add_u32_e32 v156, s9, v184
	ds_read_b128 v[72:75], v140
	ds_read_b128 v[76:79], v140 offset:1024
	ds_read_b128 v[136:139], v140 offset:2048
	ds_read_b128 v[140:143], v140 offset:3072
	ds_read_b128 v[144:147], v156
	ds_read_b128 v[148:151], v156 offset:1024
	ds_read_b128 v[152:155], v156 offset:2048
	ds_read_b128 v[156:159], v156 offset:3072
	s_add_u32 s42, s56, 0x20000
	s_addc_u32 s43, s57, 0
	s_mov_b32 m0, s59
	v_lshl_add_u64 v[222:223], s[42:43], 0, v[164:165]
	ds_read_b128 v[170:173], v185 offset:32768
	ds_read_b128 v[174:177], v185 offset:33792
	ds_read_b128 v[178:181], v185 offset:34816
	ds_read_b128 v[186:189], v185 offset:35840
	ds_read_b128 v[194:197], v185 offset:36864
	ds_read_b128 v[198:201], v185 offset:37888
	ds_read_b128 v[202:205], v185 offset:38912
	ds_read_b128 v[212:215], v185 offset:39936
	global_load_lds_dwordx4 v[222:223], off
	v_lshl_add_u64 v[222:223], s[42:43], 0, v[162:163]
	s_mov_b32 m0, s62
	s_nop 0
	global_load_lds_dwordx4 v[222:223], off
	s_waitcnt vmcnt(8)
	s_waitcnt lgkmcnt(0)
	s_barrier
	s_setprio 1
	s_waitcnt lgkmcnt(0)
	v_mfma_f32_16x16x32_bf16 v[64:67], v[72:75], v[170:173], v[64:67]
	v_mfma_f32_16x16x32_bf16 v[60:63], v[136:139], v[170:173], v[60:63]
	v_mfma_f32_16x16x32_bf16 v[124:127], v[72:75], v[178:181], v[124:127]
	v_mfma_f32_16x16x32_bf16 v[120:123], v[136:139], v[178:181], v[120:123]
	v_mfma_f32_16x16x32_bf16 v[108:111], v[72:75], v[194:197], v[108:111]
	v_mfma_f32_16x16x32_bf16 v[104:107], v[136:139], v[194:197], v[104:107]
	v_mfma_f32_16x16x32_bf16 v[92:95], v[72:75], v[202:205], v[92:95]
	v_mfma_f32_16x16x32_bf16 v[88:91], v[136:139], v[202:205], v[88:91]
	v_mfma_f32_16x16x32_bf16 v[64:67], v[76:79], v[174:177], v[64:67]
	v_mfma_f32_16x16x32_bf16 v[60:63], v[140:143], v[174:177], v[60:63]
	v_mfma_f32_16x16x32_bf16 v[124:127], v[76:79], v[186:189], v[124:127]
	v_mfma_f32_16x16x32_bf16 v[120:123], v[140:143], v[186:189], v[120:123]
	v_mfma_f32_16x16x32_bf16 v[108:111], v[76:79], v[198:201], v[108:111]
	v_mfma_f32_16x16x32_bf16 v[104:107], v[140:143], v[198:201], v[104:107]
	v_mfma_f32_16x16x32_bf16 v[92:95], v[76:79], v[212:215], v[92:95]
	v_mfma_f32_16x16x32_bf16 v[88:91], v[140:143], v[212:215], v[88:91]
	s_setprio 0
	s_setprio 1
	v_mfma_f32_16x16x32_bf16 v[132:135], v[144:147], v[170:173], v[132:135]
	v_mfma_f32_16x16x32_bf16 v[128:131], v[152:155], v[170:173], v[128:131]
	v_mfma_f32_16x16x32_bf16 v[116:119], v[144:147], v[178:181], v[116:119]
	v_mfma_f32_16x16x32_bf16 v[112:115], v[152:155], v[178:181], v[112:115]
	v_mfma_f32_16x16x32_bf16 v[100:103], v[144:147], v[194:197], v[100:103]
	v_mfma_f32_16x16x32_bf16 v[96:99], v[152:155], v[194:197], v[96:99]
	v_mfma_f32_16x16x32_bf16 v[84:87], v[144:147], v[202:205], v[84:87]
	v_mfma_f32_16x16x32_bf16 v[80:83], v[152:155], v[202:205], v[80:83]
	v_mfma_f32_16x16x32_bf16 v[132:135], v[148:151], v[174:177], v[132:135]
	v_mfma_f32_16x16x32_bf16 v[128:131], v[156:159], v[174:177], v[128:131]
	v_mfma_f32_16x16x32_bf16 v[116:119], v[148:151], v[186:189], v[116:119]
	v_mfma_f32_16x16x32_bf16 v[112:115], v[156:159], v[186:189], v[112:115]
	v_mfma_f32_16x16x32_bf16 v[100:103], v[148:151], v[198:201], v[100:103]
	v_mfma_f32_16x16x32_bf16 v[96:99], v[156:159], v[198:201], v[96:99]
	v_mfma_f32_16x16x32_bf16 v[84:87], v[148:151], v[212:215], v[84:87]
	v_mfma_f32_16x16x32_bf16 v[80:83], v[156:159], v[212:215], v[80:83]
	s_setprio 0
	s_barrier
; #define PG8_STAGE(bufoff, gbase, voff) do { _Pragma("unroll") for (int _i = 0; _i < 2; ++_i) \
;         __builtin_amdgcn_global_load_lds((const unsigned*)((const char*)(gbase) + (voff)[_i]), (LAS unsigned*)(lds + (bufoff) + ldsw + _i * 8192), 16, 0, 0); } while (0)
; #define PG8_LDA(dst, b, h) do { _Pragma("unroll") for (int m = 0; m < 4; ++m) _Pragma("unroll") for (int k = 0; k < 2; ++k) dst[m][k] = *(const LAS bf16x8*)(lds + PG8_SA(b, h) + aoff + m * 2048 + k * 1024); } while (0)
; #define PG8_MMA(ai, bj, At, Bt) do { __builtin_amdgcn_s_setprio(1); _Pragma("unroll") for (int m = 0; m < 4; ++m) _Pragma("unroll") for (int n = 0; n < 2; ++n) _Pragma("unroll") for (int k = 0; k < 2; ++k) \
;         acc[ai][bj][m][n] = __builtin_amdgcn_mfma_f32_16x16x32_bf16(Bt[n][k], At[m][k], acc[ai][bj][m][n], 0, 0, 0); __builtin_amdgcn_s_setprio(0); } while (0)
; #define PG8_WAIT_V(n) asm volatile("s_waitcnt vmcnt(" #n ")" ::: "memory")
; #define PG8_WAIT_L(n) asm volatile("s_waitcnt lgkmcnt(" #n ")" ::: "memory")
; #define PG8_BAR __builtin_amdgcn_s_barrier()
; #define PG8_SCHED __builtin_amdgcn_sched_barrier(0)
; template <class Epi, class Sched, bool ALIGN_EPI>
; __device__ __forceinline__ void gemm_phase(LAS unsigned char* lds, const Gemm g, const Sched& S, const Epi& E) {
;     ...
;         for (int t = 0; t < nt; t += 2) {
;             const bool last = (t == nt - 2);
;             const char* a1 = cA + (size_t)(t + 1) * kstep;
;     ...
;             PG8_LDA(At, 1, 1); PG8_STAGE(PG8_SB(1, 0), b3, voffB); PG8_STAGE(PG8_SB(1, 1), b3 + hstepB, voffB); PG8_STAGE(PG8_SA(1, 0), a3, voffA);
;             PG8_WAIT_V(8); PG8_WAIT_L(0); PG8_BAR; PG8_MMA(1, 0, At, B0); PG8_MMA(1, 1, At, B1); PG8_BAR; PG8_SCHED;
	s_add_i32 s8, s8, s52
	v_lshl_add_u64 v[190:191], v[190:191], 0, s[12:13]
	s_mov_b32 m0, s8
	ds_read_b128 v[170:173], v185 offset:49152
	ds_read_b128 v[174:177], v185 offset:50176
	ds_read_b128 v[178:181], v185 offset:51200
	ds_read_b128 v[186:189], v185 offset:52224
	ds_read_b128 v[194:197], v185 offset:53248
	ds_read_b128 v[198:201], v185 offset:54272
	ds_read_b128 v[202:205], v185 offset:55296
	ds_read_b128 v[212:215], v185 offset:56320
	global_load_lds_dwordx4 v[190:191], off
	s_add_i32 m0, s8, 0x2000
	s_add_u32 s42, s54, 0x20080
	v_lshl_add_u64 v[190:191], v[216:217], 0, s[12:13]
	s_addc_u32 s43, s55, 0
	s_add_i32 s8, s9, s52
	global_load_lds_dwordx4 v[190:191], off
	v_lshl_add_u64 v[190:191], s[42:43], 0, v[192:193]
	s_mov_b32 m0, s8
	s_nop 0
	global_load_lds_dwordx4 v[190:191], off
	v_lshl_add_u64 v[190:191], s[42:43], 0, v[160:161]
	s_add_i32 m0, s8, 0x2000
	s_nop 0
	global_load_lds_dwordx4 v[190:191], off
	v_lshl_add_u64 v[190:191], v[218:219], 0, s[12:13]
	s_mov_b32 m0, s66
	s_nop 0
	global_load_lds_dwordx4 v[190:191], off
	v_lshl_add_u64 v[190:191], v[220:221], 0, s[12:13]
	s_mov_b32 m0, s67
	s_nop 0
	global_load_lds_dwordx4 v[190:191], off
	s_waitcnt vmcnt(8)
	s_waitcnt lgkmcnt(0)
	s_barrier
	s_setprio 1
	s_waitcnt lgkmcnt(0)
	v_mfma_f32_16x16x32_bf16 v[68:71], v[72:75], v[170:173], v[68:71]
	v_mfma_f32_16x16x32_bf16 v[56:59], v[136:139], v[170:173], v[56:59]
	v_mfma_f32_16x16x32_bf16 v[44:47], v[72:75], v[178:181], v[44:47]
	v_mfma_f32_16x16x32_bf16 v[40:43], v[136:139], v[178:181], v[40:43]
	v_mfma_f32_16x16x32_bf16 v[28:31], v[72:75], v[194:197], v[28:31]
	v_mfma_f32_16x16x32_bf16 v[24:27], v[136:139], v[194:197], v[24:27]
	v_mfma_f32_16x16x32_bf16 v[12:15], v[72:75], v[202:205], v[12:15]
	v_mfma_f32_16x16x32_bf16 v[8:11], v[136:139], v[202:205], v[8:11]
	v_mfma_f32_16x16x32_bf16 v[68:71], v[76:79], v[174:177], v[68:71]
	v_mfma_f32_16x16x32_bf16 v[56:59], v[140:143], v[174:177], v[56:59]
	v_mfma_f32_16x16x32_bf16 v[44:47], v[76:79], v[186:189], v[44:47]
	v_mfma_f32_16x16x32_bf16 v[40:43], v[140:143], v[186:189], v[40:43]
	v_mfma_f32_16x16x32_bf16 v[28:31], v[76:79], v[198:201], v[28:31]
	v_mfma_f32_16x16x32_bf16 v[24:27], v[140:143], v[198:201], v[24:27]
	v_mfma_f32_16x16x32_bf16 v[12:15], v[76:79], v[212:215], v[12:15]
	v_mfma_f32_16x16x32_bf16 v[8:11], v[140:143], v[212:215], v[8:11]
	s_setprio 0
	s_setprio 1
	v_mfma_f32_16x16x32_bf16 v[52:55], v[144:147], v[170:173], v[52:55]
	v_mfma_f32_16x16x32_bf16 v[48:51], v[152:155], v[170:173], v[48:51]
	v_mfma_f32_16x16x32_bf16 v[36:39], v[144:147], v[178:181], v[36:39]
	v_mfma_f32_16x16x32_bf16 v[32:35], v[152:155], v[178:181], v[32:35]
	v_mfma_f32_16x16x32_bf16 v[20:23], v[144:147], v[194:197], v[20:23]
	v_mfma_f32_16x16x32_bf16 v[16:19], v[152:155], v[194:197], v[16:19]
	v_mfma_f32_16x16x32_bf16 v[4:7], v[144:147], v[202:205], v[4:7]
	v_mfma_f32_16x16x32_bf16 v[0:3], v[152:155], v[202:205], v[0:3]
	v_mfma_f32_16x16x32_bf16 v[52:55], v[148:151], v[174:177], v[52:55]
	v_mfma_f32_16x16x32_bf16 v[48:51], v[156:159], v[174:177], v[48:51]
	v_mfma_f32_16x16x32_bf16 v[36:39], v[148:151], v[186:189], v[36:39]
	v_mfma_f32_16x16x32_bf16 v[32:35], v[156:159], v[186:189], v[32:35]
	v_mfma_f32_16x16x32_bf16 v[20:23], v[148:151], v[198:201], v[20:23]
	v_mfma_f32_16x16x32_bf16 v[16:19], v[156:159], v[198:201], v[16:19]
	v_mfma_f32_16x16x32_bf16 v[4:7], v[148:151], v[212:215], v[4:7]
	v_mfma_f32_16x16x32_bf16 v[0:3], v[156:159], v[212:215], v[0:3]
	s_setprio 0
	s_barrier
	s_add_i32 vcc_lo, vcc_lo, 2
	s_add_u32 s44, s44, 0x100
	s_addc_u32 s45, s45, 0
	s_add_u32 s91, s91, 0x100
	s_addc_u32 s92, s92, 0
	s_cmp_gt_u32 vcc_lo, 5

; #define PG8_STAGE(bufoff, gbase, voff) do { _Pragma("unroll") for (int _i = 0; _i < 2; ++_i) \
;         __builtin_amdgcn_global_load_lds((const unsigned*)((const char*)(gbase) + (voff)[_i]), (LAS unsigned*)(lds + (bufoff) + ldsw + _i * 8192), 16, 0, 0); } while (0)
; #define PG8_LDA(dst, b, h) do { _Pragma("unroll") for (int m = 0; m < 4; ++m) _Pragma("unroll") for (int k = 0; k < 2; ++k) dst[m][k] = *(const LAS bf16x8*)(lds + PG8_SA(b, h) + aoff + m * 2048 + k * 1024); } while (0)
; #define PG8_LDB(dst, b, h) do { _Pragma("unroll") for (int n = 0; n < 2; ++n) _Pragma("unroll") for (int k = 0; k < 2; ++k) dst[n][k] = *(const LAS bf16x8*)(lds + PG8_SB(b, h) + boff + n * 2048 + k * 1024); } while (0)
; #define PG8_WAIT_V(n) asm volatile("s_waitcnt vmcnt(" #n ")" ::: "memory")
; #define PG8_WAIT_L(n) asm volatile("s_waitcnt lgkmcnt(" #n ")" ::: "memory")
; #define PG8_BAR __builtin_amdgcn_s_barrier()
; #define PG8_SCHED __builtin_amdgcn_sched_barrier(0)
; template <class Epi, class Sched, bool ALIGN_EPI>
; __device__ __forceinline__ void gemm_phase(LAS unsigned char* lds, const Gemm g, const Sched& S, const Epi& E) {
;     ...
;         const bool has_next = S.next(ui + 1, nxt);
;         const char* nA = has_next ? (const char*)g.A + (size_t)nxt.pm * tstepA : cA; const char* nB = has_next ? (const char*)g.Bt + (size_t)nxt.pn * tstepB : cB;
;         for (int t = 0; t < nt; t += 2) {
;             const bool last = (t == nt - 2);
;             const char* a1 = cA + (size_t)(t + 1) * kstep;
;             const char* a2 = last ? nA : cA + (size_t)(t + 2) * kstep; const char* b2 = last ? nB : cB + (size_t)(t + 2) * kstep;
;             const char* a3 = a2 + kstep; const char* b3 = b2 + kstep;
;             PG8_LDB(B0, 0, 0); PG8_LDB(B1, 0, 1); PG8_SCHED; PG8_LDA(At, 0, 0); PG8_STAGE(PG8_SA(1, 1), a1 + hstepA, voffA);
;             PG8_WAIT_V(8); PG8_WAIT_L(0); PG8_BAR; PG8_MMA(0, 0, At, B0); PG8_MMA(0, 1, At, B1); PG8_BAR; PG8_SCHED;
;             PG8_LDA(At, 0, 1); PG8_STAGE(PG8_SB(0, 0), b2, voffB); PG8_STAGE(PG8_SB(0, 1), b2 + hstepB, voffB); PG8_STAGE(PG8_SA(0, 0), a2, voffA);
;     ...
;         for (int a = 0; a < 2; ++a)
; #pragma unroll
;             for (int b = 0; b < 2; ++b)
; #pragma unroll
;                 for (int m = 0; m < 4; ++m)
; #pragma unroll
;                     for (int n = 0; n < 2; ++n) acc[a][b][m][n] = (f32x4){0.f, 0.f, 0.f, 0.f};
.LBB0_433:
	s_add_u32 s52, s6, 0x100
	s_addc_u32 s53, s7, 0
	s_mov_b32 s66, -2
	s_add_u32 s6, s4, 0x100
	s_addc_u32 s7, s5, 0
	s_add_i32 s77, 0, 0x10000
	s_cmp_eq_u32 s66, 8
	s_cselect_b32 s39, s45, s7
	s_cselect_b32 s38, s44, s6
	s_cselect_b32 s17, s21, s53
	s_cselect_b32 s16, s20, s52
	s_add_i32 s80, 0, 0x14000
	v_add_u32_e32 v156, s77, v142
	v_add_u32_e32 v172, s80, v142
	ds_read_b128 v[144:147], v156
	ds_read_b128 v[148:151], v156 offset:1024
	ds_read_b128 v[152:155], v156 offset:2048
	ds_read_b128 v[156:159], v156 offset:3072
	ds_read_b128 v[160:163], v172
	ds_read_b128 v[164:167], v172 offset:1024
	ds_read_b128 v[168:171], v172 offset:2048
	ds_read_b128 v[172:175], v172 offset:3072
	v_lshl_add_u64 v[216:217], s[4:5], 0, v[136:137]
	s_add_i32 m0, s57, 0xc000
	ds_read_b128 v[176:179], v143
	ds_read_b128 v[180:183], v143 offset:1024
	ds_read_b128 v[184:187], v143 offset:2048
	ds_read_b128 v[188:191], v143 offset:3072
	ds_read_b128 v[194:197], v143 offset:4096
	ds_read_b128 v[198:201], v143 offset:5120
	ds_read_b128 v[202:205], v143 offset:6144
	ds_read_b128 v[212:215], v143 offset:7168
	global_load_lds_dwordx4 v[216:217], off
	v_lshl_add_u64 v[216:217], s[4:5], 0, v[138:139]
	s_add_i32 m0, s57, 0xe000
	s_nop 0
	global_load_lds_dwordx4 v[216:217], off
	s_waitcnt vmcnt(8)
	s_waitcnt lgkmcnt(0)
	s_barrier
	s_setprio 1
	s_waitcnt lgkmcnt(0)
	v_mfma_f32_16x16x32_bf16 v[124:127], v[144:147], v[176:179], 0
	v_mfma_f32_16x16x32_bf16 v[120:123], v[152:155], v[176:179], 0
	v_mfma_f32_16x16x32_bf16 v[108:111], v[144:147], v[184:187], 0
	v_mfma_f32_16x16x32_bf16 v[104:107], v[152:155], v[184:187], 0
	v_mfma_f32_16x16x32_bf16 v[92:95], v[144:147], v[194:197], 0
	v_mfma_f32_16x16x32_bf16 v[88:91], v[152:155], v[194:197], 0
	v_mfma_f32_16x16x32_bf16 v[76:79], v[144:147], v[202:205], 0
	v_mfma_f32_16x16x32_bf16 v[72:75], v[152:155], v[202:205], 0
	v_mfma_f32_16x16x32_bf16 v[124:127], v[148:151], v[180:183], v[124:127]
	v_mfma_f32_16x16x32_bf16 v[120:123], v[156:159], v[180:183], v[120:123]
	v_mfma_f32_16x16x32_bf16 v[108:111], v[148:151], v[188:191], v[108:111]
	v_mfma_f32_16x16x32_bf16 v[104:107], v[156:159], v[188:191], v[104:107]
	v_mfma_f32_16x16x32_bf16 v[92:95], v[148:151], v[198:201], v[92:95]
	v_mfma_f32_16x16x32_bf16 v[88:91], v[156:159], v[198:201], v[88:91]
	v_mfma_f32_16x16x32_bf16 v[76:79], v[148:151], v[212:215], v[76:79]
	v_mfma_f32_16x16x32_bf16 v[72:75], v[156:159], v[212:215], v[72:75]
	s_setprio 0
	s_setprio 1
	v_mfma_f32_16x16x32_bf16 v[116:119], v[160:163], v[176:179], 0
	v_mfma_f32_16x16x32_bf16 v[112:115], v[168:171], v[176:179], 0
	v_mfma_f32_16x16x32_bf16 v[100:103], v[160:163], v[184:187], 0
	v_mfma_f32_16x16x32_bf16 v[96:99], v[168:171], v[184:187], 0
	v_mfma_f32_16x16x32_bf16 v[84:87], v[160:163], v[194:197], 0
	v_mfma_f32_16x16x32_bf16 v[80:83], v[168:171], v[194:197], 0
	v_mfma_f32_16x16x32_bf16 v[68:71], v[160:163], v[202:205], 0
	v_mfma_f32_16x16x32_bf16 v[64:67], v[168:171], v[202:205], 0
	v_mfma_f32_16x16x32_bf16 v[116:119], v[164:167], v[180:183], v[116:119]
	v_mfma_f32_16x16x32_bf16 v[112:115], v[172:175], v[180:183], v[112:115]
	v_mfma_f32_16x16x32_bf16 v[100:103], v[164:167], v[188:191], v[100:103]
	v_mfma_f32_16x16x32_bf16 v[96:99], v[172:175], v[188:191], v[96:99]
	v_mfma_f32_16x16x32_bf16 v[84:87], v[164:167], v[198:201], v[84:87]
	v_mfma_f32_16x16x32_bf16 v[80:83], v[172:175], v[198:201], v[80:83]
	v_mfma_f32_16x16x32_bf16 v[68:71], v[164:167], v[212:215], v[68:71]
	v_mfma_f32_16x16x32_bf16 v[64:67], v[172:175], v[212:215], v[64:67]
	s_setprio 0
	s_barrier
	s_add_i32 s4, s77, s56
	v_lshl_add_u64 v[216:217], s[16:17], 0, v[132:133]
	s_mov_b32 m0, s4
	ds_read_b128 v[176:179], v143 offset:16384
	ds_read_b128 v[180:183], v143 offset:17408
	ds_read_b128 v[184:187], v143 offset:18432
	ds_read_b128 v[188:191], v143 offset:19456
	ds_read_b128 v[194:197], v143 offset:20480
	ds_read_b128 v[198:201], v143 offset:21504
	ds_read_b128 v[202:205], v143 offset:22528
	ds_read_b128 v[212:215], v143 offset:23552
	global_load_lds_dwordx4 v[216:217], off
	s_add_i32 m0, s4, 0x2000
	s_add_u32 s4, s16, 0x30000
	v_lshl_add_u64 v[218:219], s[16:17], 0, v[128:129]
	s_addc_u32 s5, s17, 0
	s_add_i32 s77, s80, s56
	global_load_lds_dwordx4 v[218:219], off
	v_lshl_add_u64 v[220:221], s[4:5], 0, v[132:133]
	s_mov_b32 m0, s77
	v_lshl_add_u64 v[222:223], s[38:39], 0, v[130:131]
	global_load_lds_dwordx4 v[220:221], off
	v_lshl_add_u64 v[220:221], s[4:5], 0, v[128:129]
	s_add_i32 m0, s77, 0x2000
	s_nop 0
	global_load_lds_dwordx4 v[220:221], off
	v_lshl_add_u64 v[220:221], s[38:39], 0, v[134:135]
	s_mov_b32 m0, s57
	s_nop 0
	global_load_lds_dwordx4 v[220:221], off
	s_mov_b32 m0, s58
	s_nop 0
	global_load_lds_dwordx4 v[222:223], off
	s_waitcnt vmcnt(8)
	s_waitcnt lgkmcnt(0)
	s_barrier
; #define PG8_STAGE(bufoff, gbase, voff) do { _Pragma("unroll") for (int _i = 0; _i < 2; ++_i) \
;         __builtin_amdgcn_global_load_lds((const unsigned*)((const char*)(gbase) + (voff)[_i]), (LAS unsigned*)(lds + (bufoff) + ldsw + _i * 8192), 16, 0, 0); } while (0)
; #define PG8_LDA(dst, b, h) do { _Pragma("unroll") for (int m = 0; m < 4; ++m) _Pragma("unroll") for (int k = 0; k < 2; ++k) dst[m][k] = *(const LAS bf16x8*)(lds + PG8_SA(b, h) + aoff + m * 2048 + k * 1024); } while (0)
; #define PG8_LDB(dst, b, h) do { _Pragma("unroll") for (int n = 0; n < 2; ++n) _Pragma("unroll") for (int k = 0; k < 2; ++k) dst[n][k] = *(const LAS bf16x8*)(lds + PG8_SB(b, h) + boff + n * 2048 + k * 1024); } while (0)
; #define PG8_MMA(ai, bj, At, Bt) do { __builtin_amdgcn_s_setprio(1); _Pragma("unroll") for (int m = 0; m < 4; ++m) _Pragma("unroll") for (int n = 0; n < 2; ++n) _Pragma("unroll") for (int k = 0; k < 2; ++k) \
;         acc[ai][bj][m][n] = __builtin_amdgcn_mfma_f32_16x16x32_bf16(Bt[n][k], At[m][k], acc[ai][bj][m][n], 0, 0, 0); __builtin_amdgcn_s_setprio(0); } while (0)
; #define PG8_WAIT_V(n) asm volatile("s_waitcnt vmcnt(" #n ")" ::: "memory")
; #define PG8_WAIT_L(n) asm volatile("s_waitcnt lgkmcnt(" #n ")" ::: "memory")
; #define PG8_BAR __builtin_amdgcn_s_barrier()
; #define PG8_SCHED __builtin_amdgcn_sched_barrier(0)
; template <class Epi, class Sched, bool ALIGN_EPI>
; __device__ __forceinline__ void gemm_phase(LAS unsigned char* lds, const Gemm g, const Sched& S, const Epi& E) {
;     ...
;             PG8_LDA(At, 0, 1); PG8_STAGE(PG8_SB(0, 0), b2, voffB); PG8_STAGE(PG8_SB(0, 1), b2 + hstepB, voffB); PG8_STAGE(PG8_SA(0, 0), a2, voffA);
;             PG8_WAIT_V(8); PG8_WAIT_L(0); PG8_BAR; PG8_MMA(1, 0, At, B0); PG8_MMA(1, 1, At, B1); PG8_BAR; PG8_SCHED;
;             PG8_LDB(B0, 1, 0); PG8_LDB(B1, 1, 1); PG8_SCHED; PG8_LDA(At, 1, 0); PG8_STAGE(PG8_SA(0, 1), a2 + hstepA, voffA);
;             PG8_WAIT_V(8); PG8_WAIT_L(0); PG8_BAR; PG8_MMA(0, 0, At, B0); PG8_MMA(0, 1, At, B1); PG8_BAR; PG8_SCHED;
	s_setprio 1
	s_waitcnt lgkmcnt(0)
	v_mfma_f32_16x16x32_bf16 v[60:63], v[144:147], v[176:179], 0
	v_mfma_f32_16x16x32_bf16 v[56:59], v[152:155], v[176:179], 0
	v_mfma_f32_16x16x32_bf16 v[44:47], v[144:147], v[184:187], 0
	v_mfma_f32_16x16x32_bf16 v[40:43], v[152:155], v[184:187], 0
	v_mfma_f32_16x16x32_bf16 v[28:31], v[144:147], v[194:197], 0
	v_mfma_f32_16x16x32_bf16 v[24:27], v[152:155], v[194:197], 0
	v_mfma_f32_16x16x32_bf16 v[12:15], v[144:147], v[202:205], 0
	v_mfma_f32_16x16x32_bf16 v[8:11], v[152:155], v[202:205], 0
	v_mfma_f32_16x16x32_bf16 v[60:63], v[148:151], v[180:183], v[60:63]
	v_mfma_f32_16x16x32_bf16 v[56:59], v[156:159], v[180:183], v[56:59]
	v_mfma_f32_16x16x32_bf16 v[44:47], v[148:151], v[188:191], v[44:47]
	v_mfma_f32_16x16x32_bf16 v[40:43], v[156:159], v[188:191], v[40:43]
	v_mfma_f32_16x16x32_bf16 v[28:31], v[148:151], v[198:201], v[28:31]
	v_mfma_f32_16x16x32_bf16 v[24:27], v[156:159], v[198:201], v[24:27]
	v_mfma_f32_16x16x32_bf16 v[12:15], v[148:151], v[212:215], v[12:15]
	v_mfma_f32_16x16x32_bf16 v[8:11], v[156:159], v[212:215], v[8:11]
	s_setprio 0
	s_setprio 1
	v_mfma_f32_16x16x32_bf16 v[52:55], v[160:163], v[176:179], 0
	v_mfma_f32_16x16x32_bf16 v[48:51], v[168:171], v[176:179], 0
	v_mfma_f32_16x16x32_bf16 v[36:39], v[160:163], v[184:187], 0
	v_mfma_f32_16x16x32_bf16 v[32:35], v[168:171], v[184:187], 0
	v_mfma_f32_16x16x32_bf16 v[20:23], v[160:163], v[194:197], 0
	v_mfma_f32_16x16x32_bf16 v[16:19], v[168:171], v[194:197], 0
	v_mfma_f32_16x16x32_bf16 v[4:7], v[160:163], v[202:205], 0
	v_mfma_f32_16x16x32_bf16 v[0:3], v[168:171], v[202:205], 0
	v_mfma_f32_16x16x32_bf16 v[52:55], v[164:167], v[180:183], v[52:55]
	v_mfma_f32_16x16x32_bf16 v[48:51], v[172:175], v[180:183], v[48:51]
	v_mfma_f32_16x16x32_bf16 v[36:39], v[164:167], v[188:191], v[36:39]
	v_mfma_f32_16x16x32_bf16 v[32:35], v[172:175], v[188:191], v[32:35]
	v_mfma_f32_16x16x32_bf16 v[20:23], v[164:167], v[198:201], v[20:23]
	v_mfma_f32_16x16x32_bf16 v[16:19], v[172:175], v[198:201], v[16:19]
	v_mfma_f32_16x16x32_bf16 v[4:7], v[164:167], v[212:215], v[4:7]
	v_mfma_f32_16x16x32_bf16 v[0:3], v[172:175], v[212:215], v[0:3]
	s_setprio 0
	s_barrier
	s_add_i32 s77, 0, 0x18000
	s_add_i32 s80, 0, 0x1c000
	v_add_u32_e32 v156, s77, v142
	v_add_u32_e32 v172, s80, v142
	ds_read_b128 v[144:147], v156
	ds_read_b128 v[148:151], v156 offset:1024
	ds_read_b128 v[152:155], v156 offset:2048
	ds_read_b128 v[156:159], v156 offset:3072
	ds_read_b128 v[160:163], v172
	ds_read_b128 v[164:167], v172 offset:1024
	ds_read_b128 v[168:171], v172 offset:2048
	ds_read_b128 v[172:175], v172 offset:3072
	s_add_u32 s4, s38, 0x30000
	s_addc_u32 s5, s39, 0
	s_mov_b32 m0, s59
	v_lshl_add_u64 v[224:225], s[4:5], 0, v[134:135]
	ds_read_b128 v[176:179], v143 offset:32768
	ds_read_b128 v[180:183], v143 offset:33792
	ds_read_b128 v[184:187], v143 offset:34816
	ds_read_b128 v[188:191], v143 offset:35840
	ds_read_b128 v[194:197], v143 offset:36864
	ds_read_b128 v[198:201], v143 offset:37888
	ds_read_b128 v[202:205], v143 offset:38912
	ds_read_b128 v[212:215], v143 offset:39936
	global_load_lds_dwordx4 v[224:225], off
	v_lshl_add_u64 v[224:225], s[4:5], 0, v[130:131]
	s_mov_b32 m0, s62
	s_nop 0
	global_load_lds_dwordx4 v[224:225], off
	s_waitcnt vmcnt(8)
	s_waitcnt lgkmcnt(0)
	s_barrier
	s_setprio 1
	s_waitcnt lgkmcnt(0)
	v_mfma_f32_16x16x32_bf16 v[124:127], v[144:147], v[176:179], v[124:127]
	v_mfma_f32_16x16x32_bf16 v[120:123], v[152:155], v[176:179], v[120:123]
	v_mfma_f32_16x16x32_bf16 v[108:111], v[144:147], v[184:187], v[108:111]
	v_mfma_f32_16x16x32_bf16 v[104:107], v[152:155], v[184:187], v[104:107]
	v_mfma_f32_16x16x32_bf16 v[92:95], v[144:147], v[194:197], v[92:95]
	v_mfma_f32_16x16x32_bf16 v[88:91], v[152:155], v[194:197], v[88:91]
	v_mfma_f32_16x16x32_bf16 v[76:79], v[144:147], v[202:205], v[76:79]
	v_mfma_f32_16x16x32_bf16 v[72:75], v[152:155], v[202:205], v[72:75]
	v_mfma_f32_16x16x32_bf16 v[124:127], v[148:151], v[180:183], v[124:127]
	v_mfma_f32_16x16x32_bf16 v[120:123], v[156:159], v[180:183], v[120:123]
	v_mfma_f32_16x16x32_bf16 v[108:111], v[148:151], v[188:191], v[108:111]
	v_mfma_f32_16x16x32_bf16 v[104:107], v[156:159], v[188:191], v[104:107]
	v_mfma_f32_16x16x32_bf16 v[92:95], v[148:151], v[198:201], v[92:95]
	v_mfma_f32_16x16x32_bf16 v[88:91], v[156:159], v[198:201], v[88:91]
	v_mfma_f32_16x16x32_bf16 v[76:79], v[148:151], v[212:215], v[76:79]
	v_mfma_f32_16x16x32_bf16 v[72:75], v[156:159], v[212:215], v[72:75]
	s_setprio 0
	s_setprio 1
	v_mfma_f32_16x16x32_bf16 v[116:119], v[160:163], v[176:179], v[116:119]
	v_mfma_f32_16x16x32_bf16 v[112:115], v[168:171], v[176:179], v[112:115]
	v_mfma_f32_16x16x32_bf16 v[100:103], v[160:163], v[184:187], v[100:103]
	v_mfma_f32_16x16x32_bf16 v[96:99], v[168:171], v[184:187], v[96:99]
	v_mfma_f32_16x16x32_bf16 v[84:87], v[160:163], v[194:197], v[84:87]
	v_mfma_f32_16x16x32_bf16 v[80:83], v[168:171], v[194:197], v[80:83]
	v_mfma_f32_16x16x32_bf16 v[68:71], v[160:163], v[202:205], v[68:71]
	v_mfma_f32_16x16x32_bf16 v[64:67], v[168:171], v[202:205], v[64:67]
	v_mfma_f32_16x16x32_bf16 v[116:119], v[164:167], v[180:183], v[116:119]
	v_mfma_f32_16x16x32_bf16 v[112:115], v[172:175], v[180:183], v[112:115]
	v_mfma_f32_16x16x32_bf16 v[100:103], v[164:167], v[188:191], v[100:103]
	v_mfma_f32_16x16x32_bf16 v[96:99], v[172:175], v[188:191], v[96:99]
	v_mfma_f32_16x16x32_bf16 v[84:87], v[164:167], v[198:201], v[84:87]
	v_mfma_f32_16x16x32_bf16 v[80:83], v[172:175], v[198:201], v[80:83]
	v_mfma_f32_16x16x32_bf16 v[68:71], v[164:167], v[212:215], v[68:71]
	v_mfma_f32_16x16x32_bf16 v[64:67], v[172:175], v[212:215], v[64:67]
	s_setprio 0
	s_barrier
; #define PG8_STAGE(bufoff, gbase, voff) do { _Pragma("unroll") for (int _i = 0; _i < 2; ++_i) \
;         __builtin_amdgcn_global_load_lds((const unsigned*)((const char*)(gbase) + (voff)[_i]), (LAS unsigned*)(lds + (bufoff) + ldsw + _i * 8192), 16, 0, 0); } while (0)
; #define PG8_LDA(dst, b, h) do { _Pragma("unroll") for (int m = 0; m < 4; ++m) _Pragma("unroll") for (int k = 0; k < 2; ++k) dst[m][k] = *(const LAS bf16x8*)(lds + PG8_SA(b, h) + aoff + m * 2048 + k * 1024); } while (0)
; #define PG8_MMA(ai, bj, At, Bt) do { __builtin_amdgcn_s_setprio(1); _Pragma("unroll") for (int m = 0; m < 4; ++m) _Pragma("unroll") for (int n = 0; n < 2; ++n) _Pragma("unroll") for (int k = 0; k < 2; ++k) \
;         acc[ai][bj][m][n] = __builtin_amdgcn_mfma_f32_16x16x32_bf16(Bt[n][k], At[m][k], acc[ai][bj][m][n], 0, 0, 0); __builtin_amdgcn_s_setprio(0); } while (0)
; #define PG8_WAIT_V(n) asm volatile("s_waitcnt vmcnt(" #n ")" ::: "memory")
; #define PG8_WAIT_L(n) asm volatile("s_waitcnt lgkmcnt(" #n ")" ::: "memory")
; #define PG8_BAR __builtin_amdgcn_s_barrier()
; #define PG8_SCHED __builtin_amdgcn_sched_barrier(0)
; template <class Epi, class Sched, bool ALIGN_EPI>
; __device__ __forceinline__ void gemm_phase(LAS unsigned char* lds, const Gemm g, const Sched& S, const Epi& E) {
;     ...
;         for (int t = 0; t < nt; t += 2) {
;             const bool last = (t == nt - 2);
;             const char* a1 = cA + (size_t)(t + 1) * kstep;
;     ...
;             PG8_LDA(At, 1, 1); PG8_STAGE(PG8_SB(1, 0), b3, voffB); PG8_STAGE(PG8_SB(1, 1), b3 + hstepB, voffB); PG8_STAGE(PG8_SA(1, 0), a3, voffA);
;             PG8_WAIT_V(8); PG8_WAIT_L(0); PG8_BAR; PG8_MMA(1, 0, At, B0); PG8_MMA(1, 1, At, B1); PG8_BAR; PG8_SCHED;
	s_add_i32 s4, s77, s56
	v_lshl_add_u64 v[216:217], v[216:217], 0, s[12:13]
	s_mov_b32 m0, s4
	ds_read_b128 v[176:179], v143 offset:49152
	ds_read_b128 v[180:183], v143 offset:50176
	ds_read_b128 v[184:187], v143 offset:51200
	ds_read_b128 v[188:191], v143 offset:52224
	ds_read_b128 v[194:197], v143 offset:53248
	ds_read_b128 v[198:201], v143 offset:54272
	ds_read_b128 v[202:205], v143 offset:55296
	ds_read_b128 v[212:215], v143 offset:56320
	global_load_lds_dwordx4 v[216:217], off
	s_add_i32 m0, s4, 0x2000
	s_add_u32 s4, s16, 0x30080
	v_lshl_add_u64 v[216:217], v[218:219], 0, s[12:13]
	s_addc_u32 s5, s17, 0
	s_add_i32 s16, s80, s56
	global_load_lds_dwordx4 v[216:217], off
	v_lshl_add_u64 v[216:217], s[4:5], 0, v[132:133]
	s_mov_b32 m0, s16
	s_nop 0
	global_load_lds_dwordx4 v[216:217], off
	v_lshl_add_u64 v[216:217], s[4:5], 0, v[128:129]
	s_add_i32 m0, s16, 0x2000
	s_nop 0
	global_load_lds_dwordx4 v[216:217], off
	v_lshl_add_u64 v[216:217], v[220:221], 0, s[12:13]
	s_mov_b32 m0, s65
	s_nop 0
	global_load_lds_dwordx4 v[216:217], off
	v_lshl_add_u64 v[216:217], v[222:223], 0, s[12:13]
	s_mov_b32 m0, s67
	s_nop 0
	global_load_lds_dwordx4 v[216:217], off
	s_waitcnt vmcnt(8)
	s_waitcnt lgkmcnt(0)
	s_barrier
	s_setprio 1
	s_waitcnt lgkmcnt(0)
	v_mfma_f32_16x16x32_bf16 v[60:63], v[144:147], v[176:179], v[60:63]
	v_mfma_f32_16x16x32_bf16 v[56:59], v[152:155], v[176:179], v[56:59]
	v_mfma_f32_16x16x32_bf16 v[44:47], v[144:147], v[184:187], v[44:47]
	v_mfma_f32_16x16x32_bf16 v[40:43], v[152:155], v[184:187], v[40:43]
	v_mfma_f32_16x16x32_bf16 v[28:31], v[144:147], v[194:197], v[28:31]
	v_mfma_f32_16x16x32_bf16 v[24:27], v[152:155], v[194:197], v[24:27]
	v_mfma_f32_16x16x32_bf16 v[12:15], v[144:147], v[202:205], v[12:15]
	v_mfma_f32_16x16x32_bf16 v[8:11], v[152:155], v[202:205], v[8:11]
	v_mfma_f32_16x16x32_bf16 v[60:63], v[148:151], v[180:183], v[60:63]
	v_mfma_f32_16x16x32_bf16 v[56:59], v[156:159], v[180:183], v[56:59]
	v_mfma_f32_16x16x32_bf16 v[44:47], v[148:151], v[188:191], v[44:47]
	v_mfma_f32_16x16x32_bf16 v[40:43], v[156:159], v[188:191], v[40:43]
	v_mfma_f32_16x16x32_bf16 v[28:31], v[148:151], v[198:201], v[28:31]
	v_mfma_f32_16x16x32_bf16 v[24:27], v[156:159], v[198:201], v[24:27]
	v_mfma_f32_16x16x32_bf16 v[12:15], v[148:151], v[212:215], v[12:15]
	v_mfma_f32_16x16x32_bf16 v[8:11], v[156:159], v[212:215], v[8:11]
	s_setprio 0
	s_setprio 1
	v_mfma_f32_16x16x32_bf16 v[52:55], v[160:163], v[176:179], v[52:55]
	v_mfma_f32_16x16x32_bf16 v[48:51], v[168:171], v[176:179], v[48:51]
	v_mfma_f32_16x16x32_bf16 v[36:39], v[160:163], v[184:187], v[36:39]
	v_mfma_f32_16x16x32_bf16 v[32:35], v[168:171], v[184:187], v[32:35]
	v_mfma_f32_16x16x32_bf16 v[20:23], v[160:163], v[194:197], v[20:23]
	v_mfma_f32_16x16x32_bf16 v[16:19], v[168:171], v[194:197], v[16:19]
	v_mfma_f32_16x16x32_bf16 v[4:7], v[160:163], v[202:205], v[4:7]
	v_mfma_f32_16x16x32_bf16 v[0:3], v[168:171], v[202:205], v[0:3]
	v_mfma_f32_16x16x32_bf16 v[52:55], v[164:167], v[180:183], v[52:55]
	v_mfma_f32_16x16x32_bf16 v[48:51], v[172:175], v[180:183], v[48:51]
	v_mfma_f32_16x16x32_bf16 v[36:39], v[164:167], v[188:191], v[36:39]
	v_mfma_f32_16x16x32_bf16 v[32:35], v[172:175], v[188:191], v[32:35]
	v_mfma_f32_16x16x32_bf16 v[20:23], v[164:167], v[198:201], v[20:23]
	v_mfma_f32_16x16x32_bf16 v[16:19], v[172:175], v[198:201], v[16:19]
	v_mfma_f32_16x16x32_bf16 v[4:7], v[164:167], v[212:215], v[4:7]
	v_mfma_f32_16x16x32_bf16 v[0:3], v[172:175], v[212:215], v[0:3]
	s_setprio 0
	s_barrier
	s_add_i32 s66, s66, 2
	s_add_u32 s52, s52, 0x100
	s_addc_u32 s53, s53, 0
	s_cmp_gt_u32 s66, 9
	s_mov_b64 s[4:5], s[6:7]

; #define PG8_STAGE(bufoff, gbase, voff) do { _Pragma("unroll") for (int _i = 0; _i < 2; ++_i) \
;         __builtin_amdgcn_global_load_lds((const unsigned*)((const char*)(gbase) + (voff)[_i]), (LAS unsigned*)(lds + (bufoff) + ldsw + _i * 8192), 16, 0, 0); } while (0)
; #define PG8_LDA(dst, b, h) do { _Pragma("unroll") for (int m = 0; m < 4; ++m) _Pragma("unroll") for (int k = 0; k < 2; ++k) dst[m][k] = *(const LAS bf16x8*)(lds + PG8_SA(b, h) + aoff + m * 2048 + k * 1024); } while (0)
; #define PG8_LDB(dst, b, h) do { _Pragma("unroll") for (int n = 0; n < 2; ++n) _Pragma("unroll") for (int k = 0; k < 2; ++k) dst[n][k] = *(const LAS bf16x8*)(lds + PG8_SB(b, h) + boff + n * 2048 + k * 1024); } while (0)
; #define PG8_WAIT_V(n) asm volatile("s_waitcnt vmcnt(" #n ")" ::: "memory")
; #define PG8_WAIT_L(n) asm volatile("s_waitcnt lgkmcnt(" #n ")" ::: "memory")
; #define PG8_BAR __builtin_amdgcn_s_barrier()
; #define PG8_SCHED __builtin_amdgcn_sched_barrier(0)
; template <class Epi, class Sched, bool ALIGN_EPI>
; __device__ __forceinline__ void gemm_phase(LAS unsigned char* lds, const Gemm g, const Sched& S, const Epi& E) {
;     ...
;         const bool has_next = S.next(ui + 1, nxt);
;         const char* nA = has_next ? (const char*)g.A + (size_t)nxt.pm * tstepA : cA; const char* nB = has_next ? (const char*)g.Bt + (size_t)nxt.pn * tstepB : cB;
;         for (int t = 0; t < nt; t += 2) {
;             const bool last = (t == nt - 2);
;             const char* a1 = cA + (size_t)(t + 1) * kstep;
;             const char* a2 = last ? nA : cA + (size_t)(t + 2) * kstep; const char* b2 = last ? nB : cB + (size_t)(t + 2) * kstep;
;             const char* a3 = a2 + kstep; const char* b3 = b2 + kstep;
;             PG8_LDB(B0, 0, 0); PG8_LDB(B1, 0, 1); PG8_SCHED; PG8_LDA(At, 0, 0); PG8_STAGE(PG8_SA(1, 1), a1 + hstepA, voffA);
;             PG8_WAIT_V(8); PG8_WAIT_L(0); PG8_BAR; PG8_MMA(0, 0, At, B0); PG8_MMA(0, 1, At, B1); PG8_BAR; PG8_SCHED;
;             PG8_LDA(At, 0, 1); PG8_STAGE(PG8_SB(0, 0), b2, voffB); PG8_STAGE(PG8_SB(0, 1), b2 + hstepB, voffB); PG8_STAGE(PG8_SA(0, 0), a2, voffA);
;     ...
;         for (int a = 0; a < 2; ++a)
; #pragma unroll
;             for (int b = 0; b < 2; ++b)
; #pragma unroll
;                 for (int m = 0; m < 4; ++m)
; #pragma unroll
;                     for (int n = 0; n < 2; ++n) acc[a][b][m][n] = (f32x4){0.f, 0.f, 0.f, 0.f};
.LBB0_570:
	s_ashr_i32 s21, s20, 31
	s_lshl_b64 s[38:39], s[20:21], 19
	s_add_u32 s38, s22, s38
	s_addc_u32 s39, s23, s39
	s_and_b64 s[40:41], s[42:43], exec
	s_cselect_b32 s21, s39, s45
	s_cselect_b32 s86, s38, s44
	s_ashr_i32 s17, s16, 31
	s_lshl_b64 s[40:41], s[16:17], 19
	s_add_u32 s40, s50, s40
	s_addc_u32 s41, s51, s41
	s_and_b64 s[48:49], s[42:43], exec
	s_cselect_b32 s17, s41, s47
	s_cselect_b32 s87, s40, s46
	s_add_u32 s44, s44, 0x40080
	s_addc_u32 s45, s45, 0
	s_add_u32 s90, s46, 0x100
	s_addc_u32 s91, s47, 0
	s_mov_b32 s92, -2
	s_add_u32 s46, s44, 0xfffc0080
	s_addc_u32 s47, s45, -1
	s_add_i32 vcc_lo, 0, 0x10000
	s_cmp_eq_u32 s92, 12
	s_cselect_b32 s49, s21, s47
	s_cselect_b32 s48, s86, s46
	s_cselect_b32 s47, s17, s91
	s_cselect_b32 s46, s87, s90
	s_add_i32 s4, 0, 0x14000
	v_add_u32_e32 v76, vcc_lo, v162
	v_add_u32_e32 v158, s4, v162
	ds_read_b128 v[64:67], v76
	ds_read_b128 v[68:71], v76 offset:1024
	ds_read_b128 v[72:75], v76 offset:2048
	ds_read_b128 v[76:79], v76 offset:3072
	ds_read_b128 v[154:157], v158
	ds_read_b128 v[164:167], v158 offset:1024
	ds_read_b128 v[168:171], v158 offset:2048
	ds_read_b128 v[172:175], v158 offset:3072
	v_lshl_add_u64 v[158:159], s[44:45], 0, v[150:151]
	s_add_i32 m0, s54, 0xc000
	ds_read_b128 v[176:179], v163
	ds_read_b128 v[180:183], v163 offset:1024
	ds_read_b128 v[184:187], v163 offset:2048
	ds_read_b128 v[188:191], v163 offset:3072
	ds_read_b128 v[212:215], v163 offset:4096
	ds_read_b128 v[216:219], v163 offset:5120
	ds_read_b128 v[220:223], v163 offset:6144
	ds_read_b128 v[224:227], v163 offset:7168
	global_load_lds_dwordx4 v[158:159], off
	v_lshl_add_u64 v[158:159], s[44:45], 0, v[152:153]
	s_add_i32 m0, s54, 0xe000
	s_nop 0
	global_load_lds_dwordx4 v[158:159], off
	s_waitcnt vmcnt(8)
	s_waitcnt lgkmcnt(0)
	s_barrier
	s_setprio 1
	s_waitcnt lgkmcnt(0)
	v_mfma_f32_16x16x32_bf16 v[140:143], v[64:67], v[176:179], 0
	v_mfma_f32_16x16x32_bf16 v[136:139], v[72:75], v[176:179], 0
	v_mfma_f32_16x16x32_bf16 v[124:127], v[64:67], v[184:187], 0
	v_mfma_f32_16x16x32_bf16 v[120:123], v[72:75], v[184:187], 0
	v_mfma_f32_16x16x32_bf16 v[108:111], v[64:67], v[212:215], 0
	v_mfma_f32_16x16x32_bf16 v[104:107], v[72:75], v[212:215], 0
	v_mfma_f32_16x16x32_bf16 v[92:95], v[64:67], v[220:223], 0
	v_mfma_f32_16x16x32_bf16 v[88:91], v[72:75], v[220:223], 0
	v_mfma_f32_16x16x32_bf16 v[140:143], v[68:71], v[180:183], v[140:143]
	v_mfma_f32_16x16x32_bf16 v[136:139], v[76:79], v[180:183], v[136:139]
	v_mfma_f32_16x16x32_bf16 v[124:127], v[68:71], v[188:191], v[124:127]
	v_mfma_f32_16x16x32_bf16 v[120:123], v[76:79], v[188:191], v[120:123]
	v_mfma_f32_16x16x32_bf16 v[108:111], v[68:71], v[216:219], v[108:111]
	v_mfma_f32_16x16x32_bf16 v[104:107], v[76:79], v[216:219], v[104:107]
	v_mfma_f32_16x16x32_bf16 v[92:95], v[68:71], v[224:227], v[92:95]
	v_mfma_f32_16x16x32_bf16 v[88:91], v[76:79], v[224:227], v[88:91]
	s_setprio 0
	s_setprio 1
	v_mfma_f32_16x16x32_bf16 v[132:135], v[154:157], v[176:179], 0
	v_mfma_f32_16x16x32_bf16 v[128:131], v[168:171], v[176:179], 0
	v_mfma_f32_16x16x32_bf16 v[116:119], v[154:157], v[184:187], 0
	v_mfma_f32_16x16x32_bf16 v[112:115], v[168:171], v[184:187], 0
	v_mfma_f32_16x16x32_bf16 v[100:103], v[154:157], v[212:215], 0
	v_mfma_f32_16x16x32_bf16 v[96:99], v[168:171], v[212:215], 0
	v_mfma_f32_16x16x32_bf16 v[84:87], v[154:157], v[220:223], 0
	v_mfma_f32_16x16x32_bf16 v[80:83], v[168:171], v[220:223], 0
	v_mfma_f32_16x16x32_bf16 v[132:135], v[164:167], v[180:183], v[132:135]
	v_mfma_f32_16x16x32_bf16 v[128:131], v[172:175], v[180:183], v[128:131]
	v_mfma_f32_16x16x32_bf16 v[116:119], v[164:167], v[188:191], v[116:119]
	v_mfma_f32_16x16x32_bf16 v[112:115], v[172:175], v[188:191], v[112:115]
	v_mfma_f32_16x16x32_bf16 v[100:103], v[164:167], v[216:219], v[100:103]
	v_mfma_f32_16x16x32_bf16 v[96:99], v[172:175], v[216:219], v[96:99]
	v_mfma_f32_16x16x32_bf16 v[84:87], v[164:167], v[224:227], v[84:87]
	v_mfma_f32_16x16x32_bf16 v[80:83], v[172:175], v[224:227], v[80:83]
	s_setprio 0
	s_barrier
	s_add_i32 s5, vcc_lo, s53
	v_lshl_add_u64 v[158:159], s[46:47], 0, v[192:193]
	s_mov_b32 m0, s5
	ds_read_b128 v[176:179], v163 offset:16384
	ds_read_b128 v[180:183], v163 offset:17408
	ds_read_b128 v[184:187], v163 offset:18432
	ds_read_b128 v[188:191], v163 offset:19456
	ds_read_b128 v[212:215], v163 offset:20480
	ds_read_b128 v[216:219], v163 offset:21504
	ds_read_b128 v[220:223], v163 offset:22528
	ds_read_b128 v[224:227], v163 offset:23552
	global_load_lds_dwordx4 v[158:159], off
	s_add_i32 m0, s5, 0x2000
	s_add_u32 vcc_lo, s46, 0x40000
	v_lshl_add_u64 v[194:195], s[46:47], 0, v[144:145]
	s_addc_u32 vcc_hi, s47, 0
	s_add_i32 s4, s4, s53
	global_load_lds_dwordx4 v[194:195], off
	v_lshl_add_u64 v[196:197], vcc, 0, v[192:193]
	s_mov_b32 m0, s4
	v_lshl_add_u64 v[198:199], s[48:49], 0, v[146:147]
	global_load_lds_dwordx4 v[196:197], off
	v_lshl_add_u64 v[196:197], vcc, 0, v[144:145]
	s_add_i32 m0, s4, 0x2000
	s_nop 0
	global_load_lds_dwordx4 v[196:197], off
	v_lshl_add_u64 v[196:197], s[48:49], 0, v[148:149]
	s_mov_b32 m0, s54
	s_nop 0
	global_load_lds_dwordx4 v[196:197], off
	s_mov_b32 m0, s55
	s_nop 0
	global_load_lds_dwordx4 v[198:199], off
	s_waitcnt vmcnt(8)
	s_waitcnt lgkmcnt(0)
	s_barrier
; #define PG8_STAGE(bufoff, gbase, voff) do { _Pragma("unroll") for (int _i = 0; _i < 2; ++_i) \
;         __builtin_amdgcn_global_load_lds((const unsigned*)((const char*)(gbase) + (voff)[_i]), (LAS unsigned*)(lds + (bufoff) + ldsw + _i * 8192), 16, 0, 0); } while (0)
; #define PG8_LDA(dst, b, h) do { _Pragma("unroll") for (int m = 0; m < 4; ++m) _Pragma("unroll") for (int k = 0; k < 2; ++k) dst[m][k] = *(const LAS bf16x8*)(lds + PG8_SA(b, h) + aoff + m * 2048 + k * 1024); } while (0)
; #define PG8_LDB(dst, b, h) do { _Pragma("unroll") for (int n = 0; n < 2; ++n) _Pragma("unroll") for (int k = 0; k < 2; ++k) dst[n][k] = *(const LAS bf16x8*)(lds + PG8_SB(b, h) + boff + n * 2048 + k * 1024); } while (0)
; #define PG8_MMA(ai, bj, At, Bt) do { __builtin_amdgcn_s_setprio(1); _Pragma("unroll") for (int m = 0; m < 4; ++m) _Pragma("unroll") for (int n = 0; n < 2; ++n) _Pragma("unroll") for (int k = 0; k < 2; ++k) \
;         acc[ai][bj][m][n] = __builtin_amdgcn_mfma_f32_16x16x32_bf16(Bt[n][k], At[m][k], acc[ai][bj][m][n], 0, 0, 0); __builtin_amdgcn_s_setprio(0); } while (0)
; #define PG8_WAIT_V(n) asm volatile("s_waitcnt vmcnt(" #n ")" ::: "memory")
; #define PG8_WAIT_L(n) asm volatile("s_waitcnt lgkmcnt(" #n ")" ::: "memory")
; #define PG8_BAR __builtin_amdgcn_s_barrier()
; #define PG8_SCHED __builtin_amdgcn_sched_barrier(0)
; template <class Epi, class Sched, bool ALIGN_EPI>
; __device__ __forceinline__ void gemm_phase(LAS unsigned char* lds, const Gemm g, const Sched& S, const Epi& E) {
;     ...
;             PG8_LDA(At, 0, 1); PG8_STAGE(PG8_SB(0, 0), b2, voffB); PG8_STAGE(PG8_SB(0, 1), b2 + hstepB, voffB); PG8_STAGE(PG8_SA(0, 0), a2, voffA);
;             PG8_WAIT_V(8); PG8_WAIT_L(0); PG8_BAR; PG8_MMA(1, 0, At, B0); PG8_MMA(1, 1, At, B1); PG8_BAR; PG8_SCHED;
;             PG8_LDB(B0, 1, 0); PG8_LDB(B1, 1, 1); PG8_SCHED; PG8_LDA(At, 1, 0); PG8_STAGE(PG8_SA(0, 1), a2 + hstepA, voffA);
;             PG8_WAIT_V(8); PG8_WAIT_L(0); PG8_BAR; PG8_MMA(0, 0, At, B0); PG8_MMA(0, 1, At, B1); PG8_BAR; PG8_SCHED;
	s_setprio 1
	s_waitcnt lgkmcnt(0)
	v_mfma_f32_16x16x32_bf16 v[60:63], v[64:67], v[176:179], 0
	v_mfma_f32_16x16x32_bf16 v[56:59], v[72:75], v[176:179], 0
	v_mfma_f32_16x16x32_bf16 v[44:47], v[64:67], v[184:187], 0
	v_mfma_f32_16x16x32_bf16 v[40:43], v[72:75], v[184:187], 0
	v_mfma_f32_16x16x32_bf16 v[28:31], v[64:67], v[212:215], 0
	v_mfma_f32_16x16x32_bf16 v[24:27], v[72:75], v[212:215], 0
	v_mfma_f32_16x16x32_bf16 v[12:15], v[64:67], v[220:223], 0
	v_mfma_f32_16x16x32_bf16 v[8:11], v[72:75], v[220:223], 0
	v_mfma_f32_16x16x32_bf16 v[60:63], v[68:71], v[180:183], v[60:63]
	v_mfma_f32_16x16x32_bf16 v[56:59], v[76:79], v[180:183], v[56:59]
	v_mfma_f32_16x16x32_bf16 v[44:47], v[68:71], v[188:191], v[44:47]
	v_mfma_f32_16x16x32_bf16 v[40:43], v[76:79], v[188:191], v[40:43]
	v_mfma_f32_16x16x32_bf16 v[28:31], v[68:71], v[216:219], v[28:31]
	v_mfma_f32_16x16x32_bf16 v[24:27], v[76:79], v[216:219], v[24:27]
	v_mfma_f32_16x16x32_bf16 v[12:15], v[68:71], v[224:227], v[12:15]
	v_mfma_f32_16x16x32_bf16 v[8:11], v[76:79], v[224:227], v[8:11]
	s_setprio 0
	s_setprio 1
	v_mfma_f32_16x16x32_bf16 v[52:55], v[154:157], v[176:179], 0
	v_mfma_f32_16x16x32_bf16 v[48:51], v[168:171], v[176:179], 0
	v_mfma_f32_16x16x32_bf16 v[36:39], v[154:157], v[184:187], 0
	v_mfma_f32_16x16x32_bf16 v[32:35], v[168:171], v[184:187], 0
	v_mfma_f32_16x16x32_bf16 v[20:23], v[154:157], v[212:215], 0
	v_mfma_f32_16x16x32_bf16 v[16:19], v[168:171], v[212:215], 0
	v_mfma_f32_16x16x32_bf16 v[4:7], v[154:157], v[220:223], 0
	v_mfma_f32_16x16x32_bf16 v[0:3], v[168:171], v[220:223], 0
	v_mfma_f32_16x16x32_bf16 v[52:55], v[164:167], v[180:183], v[52:55]
	v_mfma_f32_16x16x32_bf16 v[48:51], v[172:175], v[180:183], v[48:51]
	v_mfma_f32_16x16x32_bf16 v[36:39], v[164:167], v[188:191], v[36:39]
	v_mfma_f32_16x16x32_bf16 v[32:35], v[172:175], v[188:191], v[32:35]
	v_mfma_f32_16x16x32_bf16 v[20:23], v[164:167], v[216:219], v[20:23]
	v_mfma_f32_16x16x32_bf16 v[16:19], v[172:175], v[216:219], v[16:19]
	v_mfma_f32_16x16x32_bf16 v[4:7], v[164:167], v[224:227], v[4:7]
	v_mfma_f32_16x16x32_bf16 v[0:3], v[172:175], v[224:227], v[0:3]
	s_setprio 0
	s_barrier
	s_add_i32 s4, 0, 0x18000
	s_add_i32 s5, 0, 0x1c000
	v_add_u32_e32 v76, s4, v162
	v_add_u32_e32 v172, s5, v162
	ds_read_b128 v[64:67], v76
	ds_read_b128 v[68:71], v76 offset:1024
	ds_read_b128 v[72:75], v76 offset:2048
	ds_read_b128 v[76:79], v76 offset:3072
	ds_read_b128 v[154:157], v172
	ds_read_b128 v[164:167], v172 offset:1024
	ds_read_b128 v[168:171], v172 offset:2048
	ds_read_b128 v[172:175], v172 offset:3072
	s_add_u32 s48, s48, 0x40000
	s_addc_u32 s49, s49, 0
	s_mov_b32 m0, s56
	v_lshl_add_u64 v[200:201], s[48:49], 0, v[148:149]
	ds_read_b128 v[176:179], v163 offset:32768
	ds_read_b128 v[180:183], v163 offset:33792
	ds_read_b128 v[184:187], v163 offset:34816
	ds_read_b128 v[188:191], v163 offset:35840
	ds_read_b128 v[212:215], v163 offset:36864
	ds_read_b128 v[216:219], v163 offset:37888
	ds_read_b128 v[220:223], v163 offset:38912
	ds_read_b128 v[224:227], v163 offset:39936
	global_load_lds_dwordx4 v[200:201], off
	v_lshl_add_u64 v[200:201], s[48:49], 0, v[146:147]
	s_mov_b32 m0, s57
	s_nop 0
	global_load_lds_dwordx4 v[200:201], off
	s_waitcnt vmcnt(8)
	s_waitcnt lgkmcnt(0)
	s_barrier
	s_setprio 1
	s_waitcnt lgkmcnt(0)
	v_mfma_f32_16x16x32_bf16 v[140:143], v[64:67], v[176:179], v[140:143]
	v_mfma_f32_16x16x32_bf16 v[136:139], v[72:75], v[176:179], v[136:139]
	v_mfma_f32_16x16x32_bf16 v[124:127], v[64:67], v[184:187], v[124:127]
	v_mfma_f32_16x16x32_bf16 v[120:123], v[72:75], v[184:187], v[120:123]
	v_mfma_f32_16x16x32_bf16 v[108:111], v[64:67], v[212:215], v[108:111]
	v_mfma_f32_16x16x32_bf16 v[104:107], v[72:75], v[212:215], v[104:107]
	v_mfma_f32_16x16x32_bf16 v[92:95], v[64:67], v[220:223], v[92:95]
	v_mfma_f32_16x16x32_bf16 v[88:91], v[72:75], v[220:223], v[88:91]
	v_mfma_f32_16x16x32_bf16 v[140:143], v[68:71], v[180:183], v[140:143]
	v_mfma_f32_16x16x32_bf16 v[136:139], v[76:79], v[180:183], v[136:139]
	v_mfma_f32_16x16x32_bf16 v[124:127], v[68:71], v[188:191], v[124:127]
	v_mfma_f32_16x16x32_bf16 v[120:123], v[76:79], v[188:191], v[120:123]
	v_mfma_f32_16x16x32_bf16 v[108:111], v[68:71], v[216:219], v[108:111]
	v_mfma_f32_16x16x32_bf16 v[104:107], v[76:79], v[216:219], v[104:107]
	v_mfma_f32_16x16x32_bf16 v[92:95], v[68:71], v[224:227], v[92:95]
	v_mfma_f32_16x16x32_bf16 v[88:91], v[76:79], v[224:227], v[88:91]
	s_setprio 0
	s_setprio 1
	v_mfma_f32_16x16x32_bf16 v[132:135], v[154:157], v[176:179], v[132:135]
	v_mfma_f32_16x16x32_bf16 v[128:131], v[168:171], v[176:179], v[128:131]
	v_mfma_f32_16x16x32_bf16 v[116:119], v[154:157], v[184:187], v[116:119]
	v_mfma_f32_16x16x32_bf16 v[112:115], v[168:171], v[184:187], v[112:115]
	v_mfma_f32_16x16x32_bf16 v[100:103], v[154:157], v[212:215], v[100:103]
	v_mfma_f32_16x16x32_bf16 v[96:99], v[168:171], v[212:215], v[96:99]
	v_mfma_f32_16x16x32_bf16 v[84:87], v[154:157], v[220:223], v[84:87]
	v_mfma_f32_16x16x32_bf16 v[80:83], v[168:171], v[220:223], v[80:83]
	v_mfma_f32_16x16x32_bf16 v[132:135], v[164:167], v[180:183], v[132:135]
	v_mfma_f32_16x16x32_bf16 v[128:131], v[172:175], v[180:183], v[128:131]
	v_mfma_f32_16x16x32_bf16 v[116:119], v[164:167], v[188:191], v[116:119]
	v_mfma_f32_16x16x32_bf16 v[112:115], v[172:175], v[188:191], v[112:115]
	v_mfma_f32_16x16x32_bf16 v[100:103], v[164:167], v[216:219], v[100:103]
	v_mfma_f32_16x16x32_bf16 v[96:99], v[172:175], v[216:219], v[96:99]
	v_mfma_f32_16x16x32_bf16 v[84:87], v[164:167], v[224:227], v[84:87]
	v_mfma_f32_16x16x32_bf16 v[80:83], v[172:175], v[224:227], v[80:83]
	s_setprio 0
	s_barrier
; #define PG8_STAGE(bufoff, gbase, voff) do { _Pragma("unroll") for (int _i = 0; _i < 2; ++_i) \
;         __builtin_amdgcn_global_load_lds((const unsigned*)((const char*)(gbase) + (voff)[_i]), (LAS unsigned*)(lds + (bufoff) + ldsw + _i * 8192), 16, 0, 0); } while (0)
; #define PG8_LDA(dst, b, h) do { _Pragma("unroll") for (int m = 0; m < 4; ++m) _Pragma("unroll") for (int k = 0; k < 2; ++k) dst[m][k] = *(const LAS bf16x8*)(lds + PG8_SA(b, h) + aoff + m * 2048 + k * 1024); } while (0)
; #define PG8_MMA(ai, bj, At, Bt) do { __builtin_amdgcn_s_setprio(1); _Pragma("unroll") for (int m = 0; m < 4; ++m) _Pragma("unroll") for (int n = 0; n < 2; ++n) _Pragma("unroll") for (int k = 0; k < 2; ++k) \
;         acc[ai][bj][m][n] = __builtin_amdgcn_mfma_f32_16x16x32_bf16(Bt[n][k], At[m][k], acc[ai][bj][m][n], 0, 0, 0); __builtin_amdgcn_s_setprio(0); } while (0)
; #define PG8_WAIT_V(n) asm volatile("s_waitcnt vmcnt(" #n ")" ::: "memory")
; #define PG8_WAIT_L(n) asm volatile("s_waitcnt lgkmcnt(" #n ")" ::: "memory")
; #define PG8_BAR __builtin_amdgcn_s_barrier()
; #define PG8_SCHED __builtin_amdgcn_sched_barrier(0)
; template <class Epi, class Sched, bool ALIGN_EPI>
; __device__ __forceinline__ void gemm_phase(LAS unsigned char* lds, const Gemm g, const Sched& S, const Epi& E) {
;     ...
;         for (int t = 0; t < nt; t += 2) {
;             const bool last = (t == nt - 2);
;             const char* a1 = cA + (size_t)(t + 1) * kstep;
;     ...
;             PG8_LDA(At, 1, 1); PG8_STAGE(PG8_SB(1, 0), b3, voffB); PG8_STAGE(PG8_SB(1, 1), b3 + hstepB, voffB); PG8_STAGE(PG8_SA(1, 0), a3, voffA);
;             PG8_WAIT_V(8); PG8_WAIT_L(0); PG8_BAR; PG8_MMA(1, 0, At, B0); PG8_MMA(1, 1, At, B1); PG8_BAR; PG8_SCHED;
	s_add_i32 s4, s4, s53
	v_lshl_add_u64 v[158:159], v[158:159], 0, s[12:13]
	s_mov_b32 m0, s4
	ds_read_b128 v[176:179], v163 offset:49152
	ds_read_b128 v[180:183], v163 offset:50176
	ds_read_b128 v[184:187], v163 offset:51200
	ds_read_b128 v[188:191], v163 offset:52224
	ds_read_b128 v[212:215], v163 offset:53248
	ds_read_b128 v[216:219], v163 offset:54272
	ds_read_b128 v[220:223], v163 offset:55296
	ds_read_b128 v[224:227], v163 offset:56320
	global_load_lds_dwordx4 v[158:159], off
	s_add_i32 m0, s4, 0x2000
	s_add_u32 s46, s46, 0x40080
	v_lshl_add_u64 v[158:159], v[194:195], 0, s[12:13]
	s_addc_u32 s47, s47, 0
	s_add_i32 s4, s5, s53
	global_load_lds_dwordx4 v[158:159], off
	v_lshl_add_u64 v[158:159], s[46:47], 0, v[192:193]
	s_mov_b32 m0, s4
	s_nop 0
	global_load_lds_dwordx4 v[158:159], off
	v_lshl_add_u64 v[158:159], s[46:47], 0, v[144:145]
	s_add_i32 m0, s4, 0x2000
	s_nop 0
	global_load_lds_dwordx4 v[158:159], off
	v_lshl_add_u64 v[158:159], v[196:197], 0, s[12:13]
	s_mov_b32 m0, s65
	s_nop 0
	global_load_lds_dwordx4 v[158:159], off
	v_lshl_add_u64 v[158:159], v[198:199], 0, s[12:13]
	s_mov_b32 m0, s66
	s_nop 0
	global_load_lds_dwordx4 v[158:159], off
	s_waitcnt vmcnt(8)
	s_waitcnt lgkmcnt(0)
	s_barrier
	s_setprio 1
	s_waitcnt lgkmcnt(0)
	v_mfma_f32_16x16x32_bf16 v[60:63], v[64:67], v[176:179], v[60:63]
	v_mfma_f32_16x16x32_bf16 v[56:59], v[72:75], v[176:179], v[56:59]
	v_mfma_f32_16x16x32_bf16 v[44:47], v[64:67], v[184:187], v[44:47]
	v_mfma_f32_16x16x32_bf16 v[40:43], v[72:75], v[184:187], v[40:43]
	v_mfma_f32_16x16x32_bf16 v[28:31], v[64:67], v[212:215], v[28:31]
	v_mfma_f32_16x16x32_bf16 v[24:27], v[72:75], v[212:215], v[24:27]
	v_mfma_f32_16x16x32_bf16 v[12:15], v[64:67], v[220:223], v[12:15]
	v_mfma_f32_16x16x32_bf16 v[8:11], v[72:75], v[220:223], v[8:11]
	v_mfma_f32_16x16x32_bf16 v[60:63], v[68:71], v[180:183], v[60:63]
	v_mfma_f32_16x16x32_bf16 v[56:59], v[76:79], v[180:183], v[56:59]
	v_mfma_f32_16x16x32_bf16 v[44:47], v[68:71], v[188:191], v[44:47]
	v_mfma_f32_16x16x32_bf16 v[40:43], v[76:79], v[188:191], v[40:43]
	v_mfma_f32_16x16x32_bf16 v[28:31], v[68:71], v[216:219], v[28:31]
	v_mfma_f32_16x16x32_bf16 v[24:27], v[76:79], v[216:219], v[24:27]
	v_mfma_f32_16x16x32_bf16 v[12:15], v[68:71], v[224:227], v[12:15]
	v_mfma_f32_16x16x32_bf16 v[8:11], v[76:79], v[224:227], v[8:11]
	s_setprio 0
	s_setprio 1
	v_mfma_f32_16x16x32_bf16 v[52:55], v[154:157], v[176:179], v[52:55]
	v_mfma_f32_16x16x32_bf16 v[48:51], v[168:171], v[176:179], v[48:51]
	v_mfma_f32_16x16x32_bf16 v[36:39], v[154:157], v[184:187], v[36:39]
	v_mfma_f32_16x16x32_bf16 v[32:35], v[168:171], v[184:187], v[32:35]
	v_mfma_f32_16x16x32_bf16 v[20:23], v[154:157], v[212:215], v[20:23]
	v_mfma_f32_16x16x32_bf16 v[16:19], v[168:171], v[212:215], v[16:19]
	v_mfma_f32_16x16x32_bf16 v[4:7], v[154:157], v[220:223], v[4:7]
	v_mfma_f32_16x16x32_bf16 v[0:3], v[168:171], v[220:223], v[0:3]
	v_mfma_f32_16x16x32_bf16 v[52:55], v[164:167], v[180:183], v[52:55]
	v_mfma_f32_16x16x32_bf16 v[48:51], v[172:175], v[180:183], v[48:51]
	v_mfma_f32_16x16x32_bf16 v[36:39], v[164:167], v[188:191], v[36:39]
	v_mfma_f32_16x16x32_bf16 v[32:35], v[172:175], v[188:191], v[32:35]
	v_mfma_f32_16x16x32_bf16 v[20:23], v[164:167], v[216:219], v[20:23]
	v_mfma_f32_16x16x32_bf16 v[16:19], v[172:175], v[216:219], v[16:19]
	v_mfma_f32_16x16x32_bf16 v[4:7], v[164:167], v[224:227], v[4:7]
	v_mfma_f32_16x16x32_bf16 v[0:3], v[172:175], v[224:227], v[0:3]
	s_setprio 0
	s_barrier
	s_add_i32 s92, s92, 2
	s_add_u32 s44, s44, 0x100
	s_addc_u32 s45, s45, 0
	s_add_u32 s90, s90, 0x100
	s_addc_u32 s91, s91, 0
	s_cmp_gt_u32 s92, 13
